# p3 scan inputs kept in f32 regs (swap), LDS-DMA loads in SGPR-base form in all 5 GEMM K-loops
# speedup vs baseline: 1.0555x; 1.0157x over previous
; #define PG8_STAGE(bufoff, gbase, voff) do { _Pragma("unroll") for (int _i = 0; _i < 2; ++_i) \
;         __builtin_amdgcn_global_load_lds((const unsigned*)((const char*)(gbase) + (voff)[_i]), (PG8_LAS unsigned*)(lds + (bufoff) + ldsw + _i * 8192), 16, 0, 0); } while (0)
; #define PG8_LDA(dst, b, h) do { _Pragma("unroll") for (int m = 0; m < 4; ++m) _Pragma("unroll") for (int k = 0; k < 2; ++k) dst[m][k] = *(const PG8_LAS bf16x8*)(lds + PG8_SA(b, h) + aoff + m * 2048 + k * 1024); } while (0)
; #define PG8_LDB(dst, b, h) do { _Pragma("unroll") for (int n = 0; n < 2; ++n) _Pragma("unroll") for (int k = 0; k < 2; ++k) dst[n][k] = *(const PG8_LAS bf16x8*)(lds + PG8_SB(b, h) + boff + n * 2048 + k * 1024); } while (0)
; #define PG8_MMA(ai, bj, At, Bt) do { __builtin_amdgcn_s_setprio(1); _Pragma("unroll") for (int m = 0; m < 4; ++m) _Pragma("unroll") for (int n = 0; n < 2; ++n) _Pragma("unroll") for (int k = 0; k < 2; ++k) \
;         acc[ai][bj][m][n] = __builtin_amdgcn_mfma_f32_16x16x32_bf16(Bt[n][k], At[m][k], acc[ai][bj][m][n], 0, 0, 0); __builtin_amdgcn_s_setprio(0); } while (0)
; #define PG8_WAIT_V(n) asm volatile("s_waitcnt vmcnt(" #n ")" ::: "memory")
; #define PG8_WAIT_L(n) asm volatile("s_waitcnt lgkmcnt(" #n ")" ::: "memory")
; #define PG8_BAR __builtin_amdgcn_s_barrier()
; #define PG8_SCHED __builtin_amdgcn_sched_barrier(0)
; template <class Epi, class Sched, bool ALIGN_EPI = false, bool SP2 = false>
; __device__ __forceinline__ void gemm_phase(PG8_LAS unsigned char* lds, const Gemm g, const Sched& S, const Epi& E) {
;     ...
;             PG8_LDB(B0, 0, 0); PG8_LDB(B1, 0, 1); PG8_SCHED; PG8_LDA(At, 0, 0); PG8_STAGE(PG8_SA(1, 1), a1 + hstep, voffA);
;             PG8_WAIT_V(8); PG8_WAIT_L(0); PG8_BAR; PG8_MMA(0, 0, At, B0); PG8_MMA(0, 1, At, B1); PG8_BAR; PG8_SCHED;
;             PG8_LDA(At, 0, 1); PG8_STAGE(PG8_SB(0, 0), b2, voffB); PG8_STAGE(PG8_SB(0, 1), b2 + hstep, voffB); PG8_STAGE(PG8_SA(0, 0), a2, voffA);
;             PG8_WAIT_V(8); PG8_WAIT_L(0); PG8_BAR; PG8_MMA(1, 0, At, B0); PG8_MMA(1, 1, At, B1); PG8_BAR; PG8_SCHED;
.LBB0_161:
	s_add_u32 s26, s90, 0xfffc0080
	s_addc_u32 s27, s91, -1
	s_add_i32 s28, 0, 0x10000
	s_cmp_eq_u32 s85, 12
	s_cselect_b32 s95, s22, s27
	s_cselect_b32 s94, s23, s26
	s_cselect_b32 s93, s36, s83
	s_cselect_b32 s92, s37, s65
	s_add_i32 s29, 0, 0x14000
	v_add_u32_e32 v154, s28, v183
	v_add_u32_e32 v187, s29, v183
	ds_read_b128 v[130:133], v154
	ds_read_b128 v[146:149], v154 offset:1024
	ds_read_b128 v[150:153], v154 offset:2048
	ds_read_b128 v[154:157], v154 offset:3072
	ds_read_b128 v[158:161], v187
	ds_read_b128 v[178:181], v187 offset:1024
	ds_read_b128 v[188:191], v187 offset:2048
	ds_read_b128 v[192:195], v187 offset:3072
	s_add_i32 m0, s58, 0xc000
	ds_read_b128 v[196:199], v186
	ds_read_b128 v[200:203], v186 offset:1024
	ds_read_b128 v[204:207], v186 offset:2048
	ds_read_b128 v[210:213], v186 offset:3072
	ds_read_b128 v[214:217], v186 offset:4096
	ds_read_b128 v[226:229], v186 offset:5120
	ds_read_b128 v[230:233], v186 offset:6144
	ds_read_b128 v[234:237], v186 offset:7168
	global_load_lds_dwordx4 v142, s[90:91]
	s_add_i32 m0, s58, 0xe000
	s_nop 0
	global_load_lds_dwordx4 v144, s[90:91]
	s_waitcnt vmcnt(8)
	s_waitcnt lgkmcnt(0)
	s_barrier
	s_setprio 1
	s_waitcnt lgkmcnt(0)
	v_mfma_f32_16x16x32_bf16 v[126:129], v[130:133], v[196:199], v[126:129]
	v_mfma_f32_16x16x32_bf16 v[114:117], v[150:153], v[196:199], v[114:117]
	v_mfma_f32_16x16x32_bf16 v[110:113], v[130:133], v[204:207], v[110:113]
	v_mfma_f32_16x16x32_bf16 v[98:101], v[150:153], v[204:207], v[98:101]
	v_mfma_f32_16x16x32_bf16 v[94:97], v[130:133], v[214:217], v[94:97]
	v_mfma_f32_16x16x32_bf16 v[82:85], v[150:153], v[214:217], v[82:85]
	v_mfma_f32_16x16x32_bf16 v[78:81], v[130:133], v[230:233], v[78:81]
	v_mfma_f32_16x16x32_bf16 v[66:69], v[150:153], v[230:233], v[66:69]
	v_mfma_f32_16x16x32_bf16 v[126:129], v[146:149], v[200:203], v[126:129]
	v_mfma_f32_16x16x32_bf16 v[114:117], v[154:157], v[200:203], v[114:117]
	v_mfma_f32_16x16x32_bf16 v[110:113], v[146:149], v[210:213], v[110:113]
	v_mfma_f32_16x16x32_bf16 v[98:101], v[154:157], v[210:213], v[98:101]
	v_mfma_f32_16x16x32_bf16 v[94:97], v[146:149], v[226:229], v[94:97]
	v_mfma_f32_16x16x32_bf16 v[82:85], v[154:157], v[226:229], v[82:85]
	v_mfma_f32_16x16x32_bf16 v[78:81], v[146:149], v[234:237], v[78:81]
	v_mfma_f32_16x16x32_bf16 v[66:69], v[154:157], v[234:237], v[66:69]
	s_setprio 0
	s_setprio 1
	v_mfma_f32_16x16x32_bf16 v[122:125], v[158:161], v[196:199], v[122:125]
	v_mfma_f32_16x16x32_bf16 v[118:121], v[188:191], v[196:199], v[118:121]
	v_mfma_f32_16x16x32_bf16 v[106:109], v[158:161], v[204:207], v[106:109]
	v_mfma_f32_16x16x32_bf16 v[102:105], v[188:191], v[204:207], v[102:105]
	v_mfma_f32_16x16x32_bf16 v[90:93], v[158:161], v[214:217], v[90:93]
	v_mfma_f32_16x16x32_bf16 v[86:89], v[188:191], v[214:217], v[86:89]
	v_mfma_f32_16x16x32_bf16 v[74:77], v[158:161], v[230:233], v[74:77]
	v_mfma_f32_16x16x32_bf16 v[70:73], v[188:191], v[230:233], v[70:73]
	v_mfma_f32_16x16x32_bf16 v[122:125], v[178:181], v[200:203], v[122:125]
	v_mfma_f32_16x16x32_bf16 v[118:121], v[192:195], v[200:203], v[118:121]
	v_mfma_f32_16x16x32_bf16 v[106:109], v[178:181], v[210:213], v[106:109]
	v_mfma_f32_16x16x32_bf16 v[102:105], v[192:195], v[210:213], v[102:105]
	v_mfma_f32_16x16x32_bf16 v[90:93], v[178:181], v[226:229], v[90:93]
	v_mfma_f32_16x16x32_bf16 v[86:89], v[192:195], v[226:229], v[86:89]
	v_mfma_f32_16x16x32_bf16 v[74:77], v[178:181], v[234:237], v[74:77]
	v_mfma_f32_16x16x32_bf16 v[70:73], v[192:195], v[234:237], v[70:73]
	s_setprio 0
	s_barrier
	s_add_i32 s26, s28, s38
	s_mov_b32 m0, s26
	ds_read_b128 v[196:199], v186 offset:16384
	ds_read_b128 v[200:203], v186 offset:17408
	ds_read_b128 v[204:207], v186 offset:18432
	ds_read_b128 v[210:213], v186 offset:19456
	ds_read_b128 v[214:217], v186 offset:20480
	ds_read_b128 v[226:229], v186 offset:21504
	ds_read_b128 v[230:233], v186 offset:22528
	ds_read_b128 v[234:237], v186 offset:23552
	global_load_lds_dwordx4 v0, s[92:93]
	s_add_i32 m0, s26, 0x2000
	s_add_u32 s26, s92, 0x40000
	s_addc_u32 s27, s93, 0
	s_add_i32 s28, s29, s38
	global_load_lds_dwordx4 v134, s[92:93]
	s_mov_b32 m0, s28
	s_nop 0
	global_load_lds_dwordx4 v0, s[26:27]
	s_add_i32 m0, s28, 0x2000
	s_nop 0
	global_load_lds_dwordx4 v134, s[26:27]
	s_mov_b32 m0, s58
	s_nop 0
	global_load_lds_dwordx4 v138, s[94:95]
	s_mov_b32 m0, s18
	s_nop 0
	global_load_lds_dwordx4 v136, s[94:95]
	s_waitcnt vmcnt(8)
	s_waitcnt lgkmcnt(0)
	s_barrier
	s_setprio 1
	s_waitcnt lgkmcnt(0)
	v_mfma_f32_16x16x32_bf16 v[62:65], v[130:133], v[196:199], v[62:65]
	v_mfma_f32_16x16x32_bf16 v[50:53], v[150:153], v[196:199], v[50:53]
	v_mfma_f32_16x16x32_bf16 v[46:49], v[130:133], v[204:207], v[46:49]
	v_mfma_f32_16x16x32_bf16 v[34:37], v[150:153], v[204:207], v[34:37]
	v_mfma_f32_16x16x32_bf16 v[30:33], v[130:133], v[214:217], v[30:33]
	v_mfma_f32_16x16x32_bf16 v[18:21], v[150:153], v[214:217], v[18:21]
	v_mfma_f32_16x16x32_bf16 v[14:17], v[130:133], v[230:233], v[14:17]
	v_mfma_f32_16x16x32_bf16 v[6:9], v[150:153], v[230:233], v[6:9]
	v_mfma_f32_16x16x32_bf16 v[62:65], v[146:149], v[200:203], v[62:65]
	v_mfma_f32_16x16x32_bf16 v[50:53], v[154:157], v[200:203], v[50:53]
	v_mfma_f32_16x16x32_bf16 v[46:49], v[146:149], v[210:213], v[46:49]
	v_mfma_f32_16x16x32_bf16 v[34:37], v[154:157], v[210:213], v[34:37]
	v_mfma_f32_16x16x32_bf16 v[30:33], v[146:149], v[226:229], v[30:33]
	v_mfma_f32_16x16x32_bf16 v[18:21], v[154:157], v[226:229], v[18:21]
	v_mfma_f32_16x16x32_bf16 v[14:17], v[146:149], v[234:237], v[14:17]
	v_mfma_f32_16x16x32_bf16 v[6:9], v[154:157], v[234:237], v[6:9]
	s_setprio 0
	s_setprio 1
	v_mfma_f32_16x16x32_bf16 v[58:61], v[158:161], v[196:199], v[58:61]
	v_mfma_f32_16x16x32_bf16 v[54:57], v[188:191], v[196:199], v[54:57]
	v_mfma_f32_16x16x32_bf16 v[42:45], v[158:161], v[204:207], v[42:45]
	v_mfma_f32_16x16x32_bf16 v[38:41], v[188:191], v[204:207], v[38:41]
	v_mfma_f32_16x16x32_bf16 v[26:29], v[158:161], v[214:217], v[26:29]
	v_mfma_f32_16x16x32_bf16 v[22:25], v[188:191], v[214:217], v[22:25]
	v_mfma_f32_16x16x32_bf16 v[10:13], v[158:161], v[230:233], v[10:13]
	v_mfma_f32_16x16x32_bf16 v[2:5], v[188:191], v[230:233], v[2:5]
	v_mfma_f32_16x16x32_bf16 v[58:61], v[178:181], v[200:203], v[58:61]
	v_mfma_f32_16x16x32_bf16 v[54:57], v[192:195], v[200:203], v[54:57]
	v_mfma_f32_16x16x32_bf16 v[42:45], v[178:181], v[210:213], v[42:45]
	v_mfma_f32_16x16x32_bf16 v[38:41], v[192:195], v[210:213], v[38:41]
	v_mfma_f32_16x16x32_bf16 v[26:29], v[178:181], v[226:229], v[26:29]
	v_mfma_f32_16x16x32_bf16 v[22:25], v[192:195], v[226:229], v[22:25]
	v_mfma_f32_16x16x32_bf16 v[10:13], v[178:181], v[234:237], v[10:13]
	v_mfma_f32_16x16x32_bf16 v[2:5], v[192:195], v[234:237], v[2:5]
	s_setprio 0
	s_barrier
; #define PG8_STAGE(bufoff, gbase, voff) do { _Pragma("unroll") for (int _i = 0; _i < 2; ++_i) \
;         __builtin_amdgcn_global_load_lds((const unsigned*)((const char*)(gbase) + (voff)[_i]), (PG8_LAS unsigned*)(lds + (bufoff) + ldsw + _i * 8192), 16, 0, 0); } while (0)
; #define PG8_LDA(dst, b, h) do { _Pragma("unroll") for (int m = 0; m < 4; ++m) _Pragma("unroll") for (int k = 0; k < 2; ++k) dst[m][k] = *(const PG8_LAS bf16x8*)(lds + PG8_SA(b, h) + aoff + m * 2048 + k * 1024); } while (0)
; #define PG8_LDB(dst, b, h) do { _Pragma("unroll") for (int n = 0; n < 2; ++n) _Pragma("unroll") for (int k = 0; k < 2; ++k) dst[n][k] = *(const PG8_LAS bf16x8*)(lds + PG8_SB(b, h) + boff + n * 2048 + k * 1024); } while (0)
; #define PG8_MMA(ai, bj, At, Bt) do { __builtin_amdgcn_s_setprio(1); _Pragma("unroll") for (int m = 0; m < 4; ++m) _Pragma("unroll") for (int n = 0; n < 2; ++n) _Pragma("unroll") for (int k = 0; k < 2; ++k) \
;         acc[ai][bj][m][n] = __builtin_amdgcn_mfma_f32_16x16x32_bf16(Bt[n][k], At[m][k], acc[ai][bj][m][n], 0, 0, 0); __builtin_amdgcn_s_setprio(0); } while (0)
; #define PG8_WAIT_V(n) asm volatile("s_waitcnt vmcnt(" #n ")" ::: "memory")
; #define PG8_WAIT_L(n) asm volatile("s_waitcnt lgkmcnt(" #n ")" ::: "memory")
; #define PG8_BAR __builtin_amdgcn_s_barrier()
; #define PG8_SCHED __builtin_amdgcn_sched_barrier(0)
; template <class Epi, class Sched, bool ALIGN_EPI = false, bool SP2 = false>
; __device__ __forceinline__ void gemm_phase(PG8_LAS unsigned char* lds, const Gemm g, const Sched& S, const Epi& E) {
;     ...
;             PG8_LDB(B0, 1, 0); PG8_LDB(B1, 1, 1); PG8_SCHED; PG8_LDA(At, 1, 0); PG8_STAGE(PG8_SA(0, 1), a2 + hstep, voffA);
;             PG8_WAIT_V(8); PG8_WAIT_L(0); PG8_BAR; PG8_MMA(0, 0, At, B0); PG8_MMA(0, 1, At, B1); PG8_BAR; PG8_SCHED;
;             PG8_LDA(At, 1, 1); PG8_STAGE(PG8_SB(1, 0), b3, voffB); PG8_STAGE(PG8_SB(1, 1), b3 + hstep, voffB); PG8_STAGE(PG8_SA(1, 0), a3, voffA);
;             PG8_WAIT_V(8); PG8_WAIT_L(0); PG8_BAR; PG8_MMA(1, 0, At, B0); PG8_MMA(1, 1, At, B1); PG8_BAR; PG8_SCHED;
	s_add_i32 s28, 0, 0x18000
	s_add_i32 s29, 0, 0x1c000
	v_add_u32_e32 v154, s28, v183
	v_add_u32_e32 v187, s29, v183
	ds_read_b128 v[130:133], v154
	ds_read_b128 v[146:149], v154 offset:1024
	ds_read_b128 v[150:153], v154 offset:2048
	ds_read_b128 v[154:157], v154 offset:3072
	ds_read_b128 v[158:161], v187
	ds_read_b128 v[178:181], v187 offset:1024
	ds_read_b128 v[188:191], v187 offset:2048
	ds_read_b128 v[192:195], v187 offset:3072
	s_add_u32 s26, s94, 0x40000
	s_addc_u32 s27, s95, 0
	s_mov_b32 m0, s19
	ds_read_b128 v[196:199], v186 offset:32768
	ds_read_b128 v[200:203], v186 offset:33792
	ds_read_b128 v[204:207], v186 offset:34816
	ds_read_b128 v[210:213], v186 offset:35840
	ds_read_b128 v[214:217], v186 offset:36864
	ds_read_b128 v[226:229], v186 offset:37888
	ds_read_b128 v[230:233], v186 offset:38912
	ds_read_b128 v[234:237], v186 offset:39936
	global_load_lds_dwordx4 v138, s[26:27]
	s_mov_b32 m0, s59
	s_nop 0
	global_load_lds_dwordx4 v136, s[26:27]
	s_waitcnt vmcnt(8)
	s_waitcnt lgkmcnt(0)
	s_barrier
	s_setprio 1
	s_waitcnt lgkmcnt(0)
	v_mfma_f32_16x16x32_bf16 v[126:129], v[130:133], v[196:199], v[126:129]
	v_mfma_f32_16x16x32_bf16 v[114:117], v[150:153], v[196:199], v[114:117]
	v_mfma_f32_16x16x32_bf16 v[110:113], v[130:133], v[204:207], v[110:113]
	v_mfma_f32_16x16x32_bf16 v[98:101], v[150:153], v[204:207], v[98:101]
	v_mfma_f32_16x16x32_bf16 v[94:97], v[130:133], v[214:217], v[94:97]
	v_mfma_f32_16x16x32_bf16 v[82:85], v[150:153], v[214:217], v[82:85]
	v_mfma_f32_16x16x32_bf16 v[78:81], v[130:133], v[230:233], v[78:81]
	v_mfma_f32_16x16x32_bf16 v[66:69], v[150:153], v[230:233], v[66:69]
	v_mfma_f32_16x16x32_bf16 v[126:129], v[146:149], v[200:203], v[126:129]
	v_mfma_f32_16x16x32_bf16 v[114:117], v[154:157], v[200:203], v[114:117]
	v_mfma_f32_16x16x32_bf16 v[110:113], v[146:149], v[210:213], v[110:113]
	v_mfma_f32_16x16x32_bf16 v[98:101], v[154:157], v[210:213], v[98:101]
	v_mfma_f32_16x16x32_bf16 v[94:97], v[146:149], v[226:229], v[94:97]
	v_mfma_f32_16x16x32_bf16 v[82:85], v[154:157], v[226:229], v[82:85]
	v_mfma_f32_16x16x32_bf16 v[78:81], v[146:149], v[234:237], v[78:81]
	v_mfma_f32_16x16x32_bf16 v[66:69], v[154:157], v[234:237], v[66:69]
	s_setprio 0
	s_setprio 1
	v_mfma_f32_16x16x32_bf16 v[122:125], v[158:161], v[196:199], v[122:125]
	v_mfma_f32_16x16x32_bf16 v[118:121], v[188:191], v[196:199], v[118:121]
	v_mfma_f32_16x16x32_bf16 v[106:109], v[158:161], v[204:207], v[106:109]
	v_mfma_f32_16x16x32_bf16 v[102:105], v[188:191], v[204:207], v[102:105]
	v_mfma_f32_16x16x32_bf16 v[90:93], v[158:161], v[214:217], v[90:93]
	v_mfma_f32_16x16x32_bf16 v[86:89], v[188:191], v[214:217], v[86:89]
	v_mfma_f32_16x16x32_bf16 v[74:77], v[158:161], v[230:233], v[74:77]
	v_mfma_f32_16x16x32_bf16 v[70:73], v[188:191], v[230:233], v[70:73]
	v_mfma_f32_16x16x32_bf16 v[122:125], v[178:181], v[200:203], v[122:125]
	v_mfma_f32_16x16x32_bf16 v[118:121], v[192:195], v[200:203], v[118:121]
	v_mfma_f32_16x16x32_bf16 v[106:109], v[178:181], v[210:213], v[106:109]
	v_mfma_f32_16x16x32_bf16 v[102:105], v[192:195], v[210:213], v[102:105]
	v_mfma_f32_16x16x32_bf16 v[90:93], v[178:181], v[226:229], v[90:93]
	v_mfma_f32_16x16x32_bf16 v[86:89], v[192:195], v[226:229], v[86:89]
	v_mfma_f32_16x16x32_bf16 v[74:77], v[178:181], v[234:237], v[74:77]
	v_mfma_f32_16x16x32_bf16 v[70:73], v[192:195], v[234:237], v[70:73]
	s_setprio 0
	s_barrier
	s_add_i32 s26, s28, s38
	s_add_u32 s100, s92, 0x80
	s_addc_u32 s101, s93, 0
	s_mov_b32 m0, s26
	ds_read_b128 v[196:199], v186 offset:49152
	ds_read_b128 v[200:203], v186 offset:50176
	ds_read_b128 v[204:207], v186 offset:51200
	ds_read_b128 v[210:213], v186 offset:52224
	ds_read_b128 v[214:217], v186 offset:53248
	ds_read_b128 v[226:229], v186 offset:54272
	ds_read_b128 v[230:233], v186 offset:55296
	ds_read_b128 v[234:237], v186 offset:56320
	global_load_lds_dwordx4 v0, s[100:101]
	s_add_i32 m0, s26, 0x2000
	s_add_u32 s26, s92, 0x40080
	s_addc_u32 s27, s93, 0
	s_add_i32 s28, s29, s38
	global_load_lds_dwordx4 v134, s[100:101]
	s_mov_b32 m0, s28
	s_nop 0
	global_load_lds_dwordx4 v0, s[26:27]
	s_add_i32 m0, s28, 0x2000
	s_add_u32 s100, s94, 0x80
	s_addc_u32 s101, s95, 0
	global_load_lds_dwordx4 v134, s[26:27]
	s_mov_b32 m0, s60
	s_nop 0
	global_load_lds_dwordx4 v138, s[100:101]
	s_mov_b32 m0, s61
	s_nop 0
	global_load_lds_dwordx4 v136, s[100:101]
	s_waitcnt vmcnt(8)
	s_waitcnt lgkmcnt(0)
	s_barrier
	s_setprio 1
	s_waitcnt lgkmcnt(0)
	v_mfma_f32_16x16x32_bf16 v[62:65], v[130:133], v[196:199], v[62:65]
	v_mfma_f32_16x16x32_bf16 v[50:53], v[150:153], v[196:199], v[50:53]
	v_mfma_f32_16x16x32_bf16 v[46:49], v[130:133], v[204:207], v[46:49]
	v_mfma_f32_16x16x32_bf16 v[34:37], v[150:153], v[204:207], v[34:37]
	v_mfma_f32_16x16x32_bf16 v[30:33], v[130:133], v[214:217], v[30:33]
	v_mfma_f32_16x16x32_bf16 v[18:21], v[150:153], v[214:217], v[18:21]
	v_mfma_f32_16x16x32_bf16 v[14:17], v[130:133], v[230:233], v[14:17]
	v_mfma_f32_16x16x32_bf16 v[6:9], v[150:153], v[230:233], v[6:9]
	v_mfma_f32_16x16x32_bf16 v[62:65], v[146:149], v[200:203], v[62:65]
	v_mfma_f32_16x16x32_bf16 v[50:53], v[154:157], v[200:203], v[50:53]
	v_mfma_f32_16x16x32_bf16 v[46:49], v[146:149], v[210:213], v[46:49]
	v_mfma_f32_16x16x32_bf16 v[34:37], v[154:157], v[210:213], v[34:37]
	v_mfma_f32_16x16x32_bf16 v[30:33], v[146:149], v[226:229], v[30:33]
	v_mfma_f32_16x16x32_bf16 v[18:21], v[154:157], v[226:229], v[18:21]
	v_mfma_f32_16x16x32_bf16 v[14:17], v[146:149], v[234:237], v[14:17]
	v_mfma_f32_16x16x32_bf16 v[6:9], v[154:157], v[234:237], v[6:9]
	s_setprio 0
	s_setprio 1
	v_mfma_f32_16x16x32_bf16 v[58:61], v[158:161], v[196:199], v[58:61]
	v_mfma_f32_16x16x32_bf16 v[54:57], v[188:191], v[196:199], v[54:57]
	v_mfma_f32_16x16x32_bf16 v[42:45], v[158:161], v[204:207], v[42:45]
	v_mfma_f32_16x16x32_bf16 v[38:41], v[188:191], v[204:207], v[38:41]
	v_mfma_f32_16x16x32_bf16 v[26:29], v[158:161], v[214:217], v[26:29]
	v_mfma_f32_16x16x32_bf16 v[22:25], v[188:191], v[214:217], v[22:25]
	v_mfma_f32_16x16x32_bf16 v[10:13], v[158:161], v[230:233], v[10:13]
	v_mfma_f32_16x16x32_bf16 v[2:5], v[188:191], v[230:233], v[2:5]
	v_mfma_f32_16x16x32_bf16 v[58:61], v[178:181], v[200:203], v[58:61]
	v_mfma_f32_16x16x32_bf16 v[54:57], v[192:195], v[200:203], v[54:57]
	v_mfma_f32_16x16x32_bf16 v[42:45], v[178:181], v[210:213], v[42:45]
	v_mfma_f32_16x16x32_bf16 v[38:41], v[192:195], v[210:213], v[38:41]
	v_mfma_f32_16x16x32_bf16 v[26:29], v[178:181], v[226:229], v[26:29]
	v_mfma_f32_16x16x32_bf16 v[22:25], v[192:195], v[226:229], v[22:25]
	v_mfma_f32_16x16x32_bf16 v[10:13], v[178:181], v[234:237], v[10:13]
	v_mfma_f32_16x16x32_bf16 v[2:5], v[192:195], v[234:237], v[2:5]
	s_setprio 0
	s_barrier
	s_add_i32 s85, s85, 2
	s_add_u32 s90, s90, 0x100
	s_addc_u32 s91, s91, 0
	s_add_u32 s65, s65, 0x100
	s_addc_u32 s83, s83, 0
	s_cmp_gt_u32 s85, 13
	s_cbranch_scc0 .LBB0_161
	s_and_b64 vcc, exec, s[80:81]
	s_cbranch_vccz .LBB0_164
	s_barrier

; #define PG8_STAGE(bufoff, gbase, voff) do { _Pragma("unroll") for (int _i = 0; _i < 2; ++_i) \
;         __builtin_amdgcn_global_load_lds((const unsigned*)((const char*)(gbase) + (voff)[_i]), (PG8_LAS unsigned*)(lds + (bufoff) + ldsw + _i * 8192), 16, 0, 0); } while (0)
; #define PG8_LDA(dst, b, h) do { _Pragma("unroll") for (int m = 0; m < 4; ++m) _Pragma("unroll") for (int k = 0; k < 2; ++k) dst[m][k] = *(const PG8_LAS bf16x8*)(lds + PG8_SA(b, h) + aoff + m * 2048 + k * 1024); } while (0)
; #define PG8_LDB(dst, b, h) do { _Pragma("unroll") for (int n = 0; n < 2; ++n) _Pragma("unroll") for (int k = 0; k < 2; ++k) dst[n][k] = *(const PG8_LAS bf16x8*)(lds + PG8_SB(b, h) + boff + n * 2048 + k * 1024); } while (0)
; #define PG8_MMA(ai, bj, At, Bt) do { __builtin_amdgcn_s_setprio(1); _Pragma("unroll") for (int m = 0; m < 4; ++m) _Pragma("unroll") for (int n = 0; n < 2; ++n) _Pragma("unroll") for (int k = 0; k < 2; ++k) \
;         acc[ai][bj][m][n] = __builtin_amdgcn_mfma_f32_16x16x32_bf16(Bt[n][k], At[m][k], acc[ai][bj][m][n], 0, 0, 0); __builtin_amdgcn_s_setprio(0); } while (0)
; #define PG8_WAIT_V(n) asm volatile("s_waitcnt vmcnt(" #n ")" ::: "memory")
; #define PG8_WAIT_L(n) asm volatile("s_waitcnt lgkmcnt(" #n ")" ::: "memory")
; #define PG8_BAR __builtin_amdgcn_s_barrier()
; #define PG8_SCHED __builtin_amdgcn_sched_barrier(0)
; template <class Epi, class Sched, bool ALIGN_EPI = false, bool SP2 = false>
; __device__ __forceinline__ void gemm_phase(PG8_LAS unsigned char* lds, const Gemm g, const Sched& S, const Epi& E) {
;     ...
;             PG8_LDB(B0, 0, 0); PG8_LDB(B1, 0, 1); PG8_SCHED; PG8_LDA(At, 0, 0); PG8_STAGE(PG8_SA(1, 1), a1 + hstep, voffA);
;             PG8_WAIT_V(8); PG8_WAIT_L(0); PG8_BAR; PG8_MMA(0, 0, At, B0); PG8_MMA(0, 1, At, B1); PG8_BAR; PG8_SCHED;
;             PG8_LDA(At, 0, 1); PG8_STAGE(PG8_SB(0, 0), b2, voffB); PG8_STAGE(PG8_SB(0, 1), b2 + hstep, voffB); PG8_STAGE(PG8_SA(0, 0), a2, voffA);
;             PG8_WAIT_V(8); PG8_WAIT_L(0); PG8_BAR; PG8_MMA(1, 0, At, B0); PG8_MMA(1, 1, At, B1); PG8_BAR; PG8_SCHED;
.LBB0_241:
	s_add_u32 s90, s88, 0x100
	s_addc_u32 s91, s89, 0
	s_add_i32 s27, 0, 0x10000
	s_cmp_eq_u32 s26, 40
	s_cselect_b32 s95, s9, s91
	s_cselect_b32 s94, s8, s90
	s_cselect_b32 s93, s87, s52
	s_cselect_b32 s92, s86, s23
	s_add_i32 s28, 0, 0x14000
	v_add_u32_e32 v142, s27, v203
	v_add_u32_e32 v184, s28, v203
	ds_read_b128 v[130:133], v142
	ds_read_b128 v[134:137], v142 offset:1024
	ds_read_b128 v[138:141], v142 offset:2048
	ds_read_b128 v[142:145], v142 offset:3072
	ds_read_b128 v[146:149], v184
	ds_read_b128 v[150:153], v184 offset:1024
	ds_read_b128 v[154:157], v184 offset:2048
	ds_read_b128 v[184:187], v184 offset:3072
	s_add_i32 m0, s39, 0xc000
	ds_read_b128 v[188:191], v205
	ds_read_b128 v[192:195], v205 offset:1024
	ds_read_b128 v[196:199], v205 offset:2048
	ds_read_b128 v[210:213], v205 offset:3072
	ds_read_b128 v[214:217], v205 offset:4096
	ds_read_b128 v[226:229], v205 offset:5120
	ds_read_b128 v[230:233], v205 offset:6144
	ds_read_b128 v[234:237], v205 offset:7168
	global_load_lds_dwordx4 v180, s[88:89]
	s_add_i32 m0, s39, 0xe000
	s_nop 0
	global_load_lds_dwordx4 v182, s[88:89]
	s_waitcnt vmcnt(8)
	s_waitcnt lgkmcnt(0)
	s_barrier
	s_setprio 1
	s_waitcnt lgkmcnt(0)
	v_mfma_f32_16x16x32_bf16 v[126:129], v[130:133], v[188:191], v[126:129]
	v_mfma_f32_16x16x32_bf16 v[122:125], v[138:141], v[188:191], v[122:125]
	v_mfma_f32_16x16x32_bf16 v[110:113], v[130:133], v[196:199], v[110:113]
	v_mfma_f32_16x16x32_bf16 v[106:109], v[138:141], v[196:199], v[106:109]
	v_mfma_f32_16x16x32_bf16 v[94:97], v[130:133], v[214:217], v[94:97]
	v_mfma_f32_16x16x32_bf16 v[90:93], v[138:141], v[214:217], v[90:93]
	v_mfma_f32_16x16x32_bf16 v[78:81], v[130:133], v[230:233], v[78:81]
	v_mfma_f32_16x16x32_bf16 v[74:77], v[138:141], v[230:233], v[74:77]
	v_mfma_f32_16x16x32_bf16 v[126:129], v[134:137], v[192:195], v[126:129]
	v_mfma_f32_16x16x32_bf16 v[122:125], v[142:145], v[192:195], v[122:125]
	v_mfma_f32_16x16x32_bf16 v[110:113], v[134:137], v[210:213], v[110:113]
	v_mfma_f32_16x16x32_bf16 v[106:109], v[142:145], v[210:213], v[106:109]
	v_mfma_f32_16x16x32_bf16 v[94:97], v[134:137], v[226:229], v[94:97]
	v_mfma_f32_16x16x32_bf16 v[90:93], v[142:145], v[226:229], v[90:93]
	v_mfma_f32_16x16x32_bf16 v[78:81], v[134:137], v[234:237], v[78:81]
	v_mfma_f32_16x16x32_bf16 v[74:77], v[142:145], v[234:237], v[74:77]
	s_setprio 0
	s_setprio 1
	v_mfma_f32_16x16x32_bf16 v[118:121], v[146:149], v[188:191], v[118:121]
	v_mfma_f32_16x16x32_bf16 v[114:117], v[154:157], v[188:191], v[114:117]
	v_mfma_f32_16x16x32_bf16 v[102:105], v[146:149], v[196:199], v[102:105]
	v_mfma_f32_16x16x32_bf16 v[98:101], v[154:157], v[196:199], v[98:101]
	v_mfma_f32_16x16x32_bf16 v[86:89], v[146:149], v[214:217], v[86:89]
	v_mfma_f32_16x16x32_bf16 v[82:85], v[154:157], v[214:217], v[82:85]
	v_mfma_f32_16x16x32_bf16 v[70:73], v[146:149], v[230:233], v[70:73]
	v_mfma_f32_16x16x32_bf16 v[66:69], v[154:157], v[230:233], v[66:69]
	v_mfma_f32_16x16x32_bf16 v[118:121], v[150:153], v[192:195], v[118:121]
	v_mfma_f32_16x16x32_bf16 v[114:117], v[184:187], v[192:195], v[114:117]
	v_mfma_f32_16x16x32_bf16 v[102:105], v[150:153], v[210:213], v[102:105]
	v_mfma_f32_16x16x32_bf16 v[98:101], v[184:187], v[210:213], v[98:101]
	v_mfma_f32_16x16x32_bf16 v[86:89], v[150:153], v[226:229], v[86:89]
	v_mfma_f32_16x16x32_bf16 v[82:85], v[184:187], v[226:229], v[82:85]
	v_mfma_f32_16x16x32_bf16 v[70:73], v[150:153], v[234:237], v[70:73]
	v_mfma_f32_16x16x32_bf16 v[66:69], v[184:187], v[234:237], v[66:69]
	s_setprio 0
	s_barrier
	s_add_i32 s27, s27, s38
	s_mov_b32 m0, s27
	ds_read_b128 v[188:191], v205 offset:16384
	ds_read_b128 v[192:195], v205 offset:17408
	ds_read_b128 v[196:199], v205 offset:18432
	ds_read_b128 v[210:213], v205 offset:19456
	ds_read_b128 v[214:217], v205 offset:20480
	ds_read_b128 v[226:229], v205 offset:21504
	ds_read_b128 v[230:233], v205 offset:22528
	ds_read_b128 v[234:237], v205 offset:23552
	global_load_lds_dwordx4 v0, s[92:93]
	s_add_i32 m0, s27, 0x2000
	s_add_u32 s88, s92, 0xb0000
	s_addc_u32 s89, s93, 0
	s_add_i32 s27, s28, s38
	global_load_lds_dwordx4 v158, s[92:93]
	s_mov_b32 m0, s27
	s_nop 0
	global_load_lds_dwordx4 v0, s[88:89]
	s_add_i32 m0, s27, 0x2000
	s_nop 0
	global_load_lds_dwordx4 v158, s[88:89]
	s_mov_b32 m0, s39
	s_nop 0
	global_load_lds_dwordx4 v178, s[94:95]
	s_mov_b32 m0, s54
	s_nop 0
	global_load_lds_dwordx4 v160, s[94:95]
	s_waitcnt vmcnt(8)
	s_waitcnt lgkmcnt(0)
	s_barrier
	s_setprio 1
	s_waitcnt lgkmcnt(0)
	v_mfma_f32_16x16x32_bf16 v[62:65], v[130:133], v[188:191], v[62:65]
	v_mfma_f32_16x16x32_bf16 v[58:61], v[138:141], v[188:191], v[58:61]
	v_mfma_f32_16x16x32_bf16 v[46:49], v[130:133], v[196:199], v[46:49]
	v_mfma_f32_16x16x32_bf16 v[42:45], v[138:141], v[196:199], v[42:45]
	v_mfma_f32_16x16x32_bf16 v[30:33], v[130:133], v[214:217], v[30:33]
	v_mfma_f32_16x16x32_bf16 v[26:29], v[138:141], v[214:217], v[26:29]
	v_mfma_f32_16x16x32_bf16 v[14:17], v[130:133], v[230:233], v[14:17]
	v_mfma_f32_16x16x32_bf16 v[10:13], v[138:141], v[230:233], v[10:13]
	v_mfma_f32_16x16x32_bf16 v[62:65], v[134:137], v[192:195], v[62:65]
	v_mfma_f32_16x16x32_bf16 v[58:61], v[142:145], v[192:195], v[58:61]
	v_mfma_f32_16x16x32_bf16 v[46:49], v[134:137], v[210:213], v[46:49]
	v_mfma_f32_16x16x32_bf16 v[42:45], v[142:145], v[210:213], v[42:45]
	v_mfma_f32_16x16x32_bf16 v[30:33], v[134:137], v[226:229], v[30:33]
	v_mfma_f32_16x16x32_bf16 v[26:29], v[142:145], v[226:229], v[26:29]
	v_mfma_f32_16x16x32_bf16 v[14:17], v[134:137], v[234:237], v[14:17]
	v_mfma_f32_16x16x32_bf16 v[10:13], v[142:145], v[234:237], v[10:13]
	s_setprio 0
	s_setprio 1
	v_mfma_f32_16x16x32_bf16 v[54:57], v[146:149], v[188:191], v[54:57]
	v_mfma_f32_16x16x32_bf16 v[50:53], v[154:157], v[188:191], v[50:53]
	v_mfma_f32_16x16x32_bf16 v[38:41], v[146:149], v[196:199], v[38:41]
	v_mfma_f32_16x16x32_bf16 v[34:37], v[154:157], v[196:199], v[34:37]
	v_mfma_f32_16x16x32_bf16 v[22:25], v[146:149], v[214:217], v[22:25]
	v_mfma_f32_16x16x32_bf16 v[18:21], v[154:157], v[214:217], v[18:21]
	v_mfma_f32_16x16x32_bf16 v[6:9], v[146:149], v[230:233], v[6:9]
	v_mfma_f32_16x16x32_bf16 v[2:5], v[154:157], v[230:233], v[2:5]
	v_mfma_f32_16x16x32_bf16 v[54:57], v[150:153], v[192:195], v[54:57]
	v_mfma_f32_16x16x32_bf16 v[50:53], v[184:187], v[192:195], v[50:53]
	v_mfma_f32_16x16x32_bf16 v[38:41], v[150:153], v[210:213], v[38:41]
	v_mfma_f32_16x16x32_bf16 v[34:37], v[184:187], v[210:213], v[34:37]
	v_mfma_f32_16x16x32_bf16 v[22:25], v[150:153], v[226:229], v[22:25]
	v_mfma_f32_16x16x32_bf16 v[18:21], v[184:187], v[226:229], v[18:21]
	v_mfma_f32_16x16x32_bf16 v[6:9], v[150:153], v[234:237], v[6:9]
	v_mfma_f32_16x16x32_bf16 v[2:5], v[184:187], v[234:237], v[2:5]
	s_setprio 0
	s_barrier
; #define PG8_STAGE(bufoff, gbase, voff) do { _Pragma("unroll") for (int _i = 0; _i < 2; ++_i) \
;         __builtin_amdgcn_global_load_lds((const unsigned*)((const char*)(gbase) + (voff)[_i]), (PG8_LAS unsigned*)(lds + (bufoff) + ldsw + _i * 8192), 16, 0, 0); } while (0)
; #define PG8_LDA(dst, b, h) do { _Pragma("unroll") for (int m = 0; m < 4; ++m) _Pragma("unroll") for (int k = 0; k < 2; ++k) dst[m][k] = *(const PG8_LAS bf16x8*)(lds + PG8_SA(b, h) + aoff + m * 2048 + k * 1024); } while (0)
; #define PG8_LDB(dst, b, h) do { _Pragma("unroll") for (int n = 0; n < 2; ++n) _Pragma("unroll") for (int k = 0; k < 2; ++k) dst[n][k] = *(const PG8_LAS bf16x8*)(lds + PG8_SB(b, h) + boff + n * 2048 + k * 1024); } while (0)
; #define PG8_MMA(ai, bj, At, Bt) do { __builtin_amdgcn_s_setprio(1); _Pragma("unroll") for (int m = 0; m < 4; ++m) _Pragma("unroll") for (int n = 0; n < 2; ++n) _Pragma("unroll") for (int k = 0; k < 2; ++k) \
;         acc[ai][bj][m][n] = __builtin_amdgcn_mfma_f32_16x16x32_bf16(Bt[n][k], At[m][k], acc[ai][bj][m][n], 0, 0, 0); __builtin_amdgcn_s_setprio(0); } while (0)
; #define PG8_WAIT_V(n) asm volatile("s_waitcnt vmcnt(" #n ")" ::: "memory")
; #define PG8_WAIT_L(n) asm volatile("s_waitcnt lgkmcnt(" #n ")" ::: "memory")
; #define PG8_BAR __builtin_amdgcn_s_barrier()
; #define PG8_SCHED __builtin_amdgcn_sched_barrier(0)
; template <class Epi, class Sched, bool ALIGN_EPI = false, bool SP2 = false>
; __device__ __forceinline__ void gemm_phase(PG8_LAS unsigned char* lds, const Gemm g, const Sched& S, const Epi& E) {
;     ...
;             PG8_LDB(B0, 1, 0); PG8_LDB(B1, 1, 1); PG8_SCHED; PG8_LDA(At, 1, 0); PG8_STAGE(PG8_SA(0, 1), a2 + hstep, voffA);
;             PG8_WAIT_V(8); PG8_WAIT_L(0); PG8_BAR; PG8_MMA(0, 0, At, B0); PG8_MMA(0, 1, At, B1); PG8_BAR; PG8_SCHED;
;             PG8_LDA(At, 1, 1); PG8_STAGE(PG8_SB(1, 0), b3, voffB); PG8_STAGE(PG8_SB(1, 1), b3 + hstep, voffB); PG8_STAGE(PG8_SA(1, 0), a3, voffA);
;             PG8_WAIT_V(8); PG8_WAIT_L(0); PG8_BAR; PG8_MMA(1, 0, At, B0); PG8_MMA(1, 1, At, B1); PG8_BAR; PG8_SCHED;
	s_add_i32 s27, 0, 0x18000
	s_add_i32 s28, 0, 0x1c000
	v_add_u32_e32 v142, s27, v203
	v_add_u32_e32 v184, s28, v203
	ds_read_b128 v[130:133], v142
	ds_read_b128 v[134:137], v142 offset:1024
	ds_read_b128 v[138:141], v142 offset:2048
	ds_read_b128 v[142:145], v142 offset:3072
	ds_read_b128 v[146:149], v184
	ds_read_b128 v[150:153], v184 offset:1024
	ds_read_b128 v[154:157], v184 offset:2048
	ds_read_b128 v[184:187], v184 offset:3072
	s_add_u32 s88, s94, 0xb0000
	s_addc_u32 s89, s95, 0
	s_mov_b32 m0, s55
	ds_read_b128 v[188:191], v205 offset:32768
	ds_read_b128 v[192:195], v205 offset:33792
	ds_read_b128 v[196:199], v205 offset:34816
	ds_read_b128 v[210:213], v205 offset:35840
	ds_read_b128 v[214:217], v205 offset:36864
	ds_read_b128 v[226:229], v205 offset:37888
	ds_read_b128 v[230:233], v205 offset:38912
	ds_read_b128 v[234:237], v205 offset:39936
	global_load_lds_dwordx4 v178, s[88:89]
	s_mov_b32 m0, s58
	s_nop 0
	global_load_lds_dwordx4 v160, s[88:89]
	s_waitcnt vmcnt(8)
	s_waitcnt lgkmcnt(0)
	s_barrier
	s_setprio 1
	s_waitcnt lgkmcnt(0)
	v_mfma_f32_16x16x32_bf16 v[126:129], v[130:133], v[188:191], v[126:129]
	v_mfma_f32_16x16x32_bf16 v[122:125], v[138:141], v[188:191], v[122:125]
	v_mfma_f32_16x16x32_bf16 v[110:113], v[130:133], v[196:199], v[110:113]
	v_mfma_f32_16x16x32_bf16 v[106:109], v[138:141], v[196:199], v[106:109]
	v_mfma_f32_16x16x32_bf16 v[94:97], v[130:133], v[214:217], v[94:97]
	v_mfma_f32_16x16x32_bf16 v[90:93], v[138:141], v[214:217], v[90:93]
	v_mfma_f32_16x16x32_bf16 v[78:81], v[130:133], v[230:233], v[78:81]
	v_mfma_f32_16x16x32_bf16 v[74:77], v[138:141], v[230:233], v[74:77]
	v_mfma_f32_16x16x32_bf16 v[126:129], v[134:137], v[192:195], v[126:129]
	v_mfma_f32_16x16x32_bf16 v[122:125], v[142:145], v[192:195], v[122:125]
	v_mfma_f32_16x16x32_bf16 v[110:113], v[134:137], v[210:213], v[110:113]
	v_mfma_f32_16x16x32_bf16 v[106:109], v[142:145], v[210:213], v[106:109]
	v_mfma_f32_16x16x32_bf16 v[94:97], v[134:137], v[226:229], v[94:97]
	v_mfma_f32_16x16x32_bf16 v[90:93], v[142:145], v[226:229], v[90:93]
	v_mfma_f32_16x16x32_bf16 v[78:81], v[134:137], v[234:237], v[78:81]
	v_mfma_f32_16x16x32_bf16 v[74:77], v[142:145], v[234:237], v[74:77]
	s_setprio 0
	s_setprio 1
	v_mfma_f32_16x16x32_bf16 v[118:121], v[146:149], v[188:191], v[118:121]
	v_mfma_f32_16x16x32_bf16 v[114:117], v[154:157], v[188:191], v[114:117]
	v_mfma_f32_16x16x32_bf16 v[102:105], v[146:149], v[196:199], v[102:105]
	v_mfma_f32_16x16x32_bf16 v[98:101], v[154:157], v[196:199], v[98:101]
	v_mfma_f32_16x16x32_bf16 v[86:89], v[146:149], v[214:217], v[86:89]
	v_mfma_f32_16x16x32_bf16 v[82:85], v[154:157], v[214:217], v[82:85]
	v_mfma_f32_16x16x32_bf16 v[70:73], v[146:149], v[230:233], v[70:73]
	v_mfma_f32_16x16x32_bf16 v[66:69], v[154:157], v[230:233], v[66:69]
	v_mfma_f32_16x16x32_bf16 v[118:121], v[150:153], v[192:195], v[118:121]
	v_mfma_f32_16x16x32_bf16 v[114:117], v[184:187], v[192:195], v[114:117]
	v_mfma_f32_16x16x32_bf16 v[102:105], v[150:153], v[210:213], v[102:105]
	v_mfma_f32_16x16x32_bf16 v[98:101], v[184:187], v[210:213], v[98:101]
	v_mfma_f32_16x16x32_bf16 v[86:89], v[150:153], v[226:229], v[86:89]
	v_mfma_f32_16x16x32_bf16 v[82:85], v[184:187], v[226:229], v[82:85]
	v_mfma_f32_16x16x32_bf16 v[70:73], v[150:153], v[234:237], v[70:73]
	v_mfma_f32_16x16x32_bf16 v[66:69], v[184:187], v[234:237], v[66:69]
	s_setprio 0
	s_barrier
	s_add_i32 s27, s27, s38
	s_mov_b32 m0, s27
	ds_read_b128 v[188:191], v205 offset:49152
	ds_read_b128 v[192:195], v205 offset:50176
	ds_read_b128 v[196:199], v205 offset:51200
	ds_read_b128 v[210:213], v205 offset:52224
	ds_read_b128 v[214:217], v205 offset:53248
	ds_read_b128 v[226:229], v205 offset:54272
	ds_read_b128 v[230:233], v205 offset:55296
	ds_read_b128 v[234:237], v205 offset:56320
	s_add_u32 s100, s92, 0x80
	s_addc_u32 s101, s93, 0
	global_load_lds_dwordx4 v0, s[100:101]
	s_add_i32 m0, s27, 0x2000
	s_add_u32 s88, s92, 0xb0080
	s_addc_u32 s89, s93, 0
	s_add_i32 s27, s28, s38
	s_add_u32 s100, s92, 0x80
	s_addc_u32 s101, s93, 0
	global_load_lds_dwordx4 v158, s[100:101]
	s_mov_b32 m0, s27
	s_nop 0
	global_load_lds_dwordx4 v0, s[88:89]
	s_add_i32 m0, s27, 0x2000
	s_nop 0
	global_load_lds_dwordx4 v158, s[88:89]
	s_mov_b32 m0, s62
	s_nop 0
	s_add_u32 s100, s94, 0x80
	s_addc_u32 s101, s95, 0
	global_load_lds_dwordx4 v178, s[100:101]
	s_mov_b32 m0, s63
	s_nop 0
	s_add_u32 s100, s94, 0x80
	s_addc_u32 s101, s95, 0
	global_load_lds_dwordx4 v160, s[100:101]
	s_waitcnt vmcnt(8)
	s_waitcnt lgkmcnt(0)
	s_barrier
	s_setprio 1
	s_waitcnt lgkmcnt(0)
	v_mfma_f32_16x16x32_bf16 v[62:65], v[130:133], v[188:191], v[62:65]
	v_mfma_f32_16x16x32_bf16 v[58:61], v[138:141], v[188:191], v[58:61]
	v_mfma_f32_16x16x32_bf16 v[46:49], v[130:133], v[196:199], v[46:49]
	v_mfma_f32_16x16x32_bf16 v[42:45], v[138:141], v[196:199], v[42:45]
	v_mfma_f32_16x16x32_bf16 v[30:33], v[130:133], v[214:217], v[30:33]
	v_mfma_f32_16x16x32_bf16 v[26:29], v[138:141], v[214:217], v[26:29]
	v_mfma_f32_16x16x32_bf16 v[14:17], v[130:133], v[230:233], v[14:17]
	v_mfma_f32_16x16x32_bf16 v[10:13], v[138:141], v[230:233], v[10:13]
	v_mfma_f32_16x16x32_bf16 v[62:65], v[134:137], v[192:195], v[62:65]
	v_mfma_f32_16x16x32_bf16 v[58:61], v[142:145], v[192:195], v[58:61]
	v_mfma_f32_16x16x32_bf16 v[46:49], v[134:137], v[210:213], v[46:49]
	v_mfma_f32_16x16x32_bf16 v[42:45], v[142:145], v[210:213], v[42:45]
	v_mfma_f32_16x16x32_bf16 v[30:33], v[134:137], v[226:229], v[30:33]
	v_mfma_f32_16x16x32_bf16 v[26:29], v[142:145], v[226:229], v[26:29]
	v_mfma_f32_16x16x32_bf16 v[14:17], v[134:137], v[234:237], v[14:17]
	v_mfma_f32_16x16x32_bf16 v[10:13], v[142:145], v[234:237], v[10:13]
	s_setprio 0
	s_setprio 1
	v_mfma_f32_16x16x32_bf16 v[54:57], v[146:149], v[188:191], v[54:57]
	v_mfma_f32_16x16x32_bf16 v[50:53], v[154:157], v[188:191], v[50:53]
	v_mfma_f32_16x16x32_bf16 v[38:41], v[146:149], v[196:199], v[38:41]
	v_mfma_f32_16x16x32_bf16 v[34:37], v[154:157], v[196:199], v[34:37]
	v_mfma_f32_16x16x32_bf16 v[22:25], v[146:149], v[214:217], v[22:25]
	v_mfma_f32_16x16x32_bf16 v[18:21], v[154:157], v[214:217], v[18:21]
	v_mfma_f32_16x16x32_bf16 v[6:9], v[146:149], v[230:233], v[6:9]
	v_mfma_f32_16x16x32_bf16 v[2:5], v[154:157], v[230:233], v[2:5]
	v_mfma_f32_16x16x32_bf16 v[54:57], v[150:153], v[192:195], v[54:57]
	v_mfma_f32_16x16x32_bf16 v[50:53], v[184:187], v[192:195], v[50:53]
	v_mfma_f32_16x16x32_bf16 v[38:41], v[150:153], v[210:213], v[38:41]
	v_mfma_f32_16x16x32_bf16 v[34:37], v[184:187], v[210:213], v[34:37]
	v_mfma_f32_16x16x32_bf16 v[22:25], v[150:153], v[226:229], v[22:25]
	v_mfma_f32_16x16x32_bf16 v[18:21], v[184:187], v[226:229], v[18:21]
	v_mfma_f32_16x16x32_bf16 v[6:9], v[150:153], v[234:237], v[6:9]
	v_mfma_f32_16x16x32_bf16 v[2:5], v[184:187], v[234:237], v[2:5]
	s_setprio 0
	s_barrier
	s_add_i32 s26, s26, 2
	s_add_u32 s23, s23, 0x100
	s_addc_u32 s52, s52, 0
	s_cmp_gt_u32 s26, 41
	s_mov_b64 s[88:89], s[90:91]
	s_cbranch_scc0 .LBB0_241
	s_and_b64 vcc, exec, s[82:83]
	s_cbranch_vccz .LBB0_244
	s_barrier

; #define PG8_STAGE(bufoff, gbase, voff) do { _Pragma("unroll") for (int _i = 0; _i < 2; ++_i) \
;         __builtin_amdgcn_global_load_lds((const unsigned*)((const char*)(gbase) + (voff)[_i]), (PG8_LAS unsigned*)(lds + (bufoff) + ldsw + _i * 8192), 16, 0, 0); } while (0)
; #define PG8_LDA(dst, b, h) do { _Pragma("unroll") for (int m = 0; m < 4; ++m) _Pragma("unroll") for (int k = 0; k < 2; ++k) dst[m][k] = *(const PG8_LAS bf16x8*)(lds + PG8_SA(b, h) + aoff + m * 2048 + k * 1024); } while (0)
; #define PG8_LDB(dst, b, h) do { _Pragma("unroll") for (int n = 0; n < 2; ++n) _Pragma("unroll") for (int k = 0; k < 2; ++k) dst[n][k] = *(const PG8_LAS bf16x8*)(lds + PG8_SB(b, h) + boff + n * 2048 + k * 1024); } while (0)
; #define PG8_MMA(ai, bj, At, Bt) do { __builtin_amdgcn_s_setprio(1); _Pragma("unroll") for (int m = 0; m < 4; ++m) _Pragma("unroll") for (int n = 0; n < 2; ++n) _Pragma("unroll") for (int k = 0; k < 2; ++k) \
;         acc[ai][bj][m][n] = __builtin_amdgcn_mfma_f32_16x16x32_bf16(Bt[n][k], At[m][k], acc[ai][bj][m][n], 0, 0, 0); __builtin_amdgcn_s_setprio(0); } while (0)
; #define PG8_WAIT_V(n) asm volatile("s_waitcnt vmcnt(" #n ")" ::: "memory")
; #define PG8_WAIT_L(n) asm volatile("s_waitcnt lgkmcnt(" #n ")" ::: "memory")
; #define PG8_BAR __builtin_amdgcn_s_barrier()
; #define PG8_SCHED __builtin_amdgcn_sched_barrier(0)
; template <class Epi, class Sched, bool ALIGN_EPI = false, bool SP2 = false>
; __device__ __forceinline__ void gemm_phase(PG8_LAS unsigned char* lds, const Gemm g, const Sched& S, const Epi& E) {
;     ...
;             PG8_LDB(B0, 0, 0); PG8_LDB(B1, 0, 1); PG8_SCHED; PG8_LDA(At, 0, 0); PG8_STAGE(PG8_SA(1, 1), a1 + hstep, voffA);
;             PG8_WAIT_V(8); PG8_WAIT_L(0); PG8_BAR; PG8_MMA(0, 0, At, B0); PG8_MMA(0, 1, At, B1); PG8_BAR; PG8_SCHED;
;             PG8_LDA(At, 0, 1); PG8_STAGE(PG8_SB(0, 0), b2, voffB); PG8_STAGE(PG8_SB(0, 1), b2 + hstep, voffB); PG8_STAGE(PG8_SA(0, 0), a2, voffA);
;             PG8_WAIT_V(8); PG8_WAIT_L(0); PG8_BAR; PG8_MMA(1, 0, At, B0); PG8_MMA(1, 1, At, B1); PG8_BAR; PG8_SCHED;
.LBB0_340:
	s_add_u32 s26, s6, 0xfffc0080
	s_addc_u32 s27, s7, -1
	s_add_i32 s28, 0, 0x10000
	s_cmp_eq_u32 s96, 12
	s_cselect_b32 s93, s22, s27
	s_cselect_b32 s92, s23, s26
	s_cselect_b32 s91, s83, s95
	s_cselect_b32 s90, s85, s94
	s_add_i32 s29, 0, 0x14000
	v_add_u32_e32 v158, s28, v191
	v_add_u32_e32 v194, s29, v191
	ds_read_b128 v[2:5], v158
	ds_read_b128 v[6:9], v158 offset:1024
	ds_read_b128 v[138:141], v158 offset:2048
	ds_read_b128 v[158:161], v158 offset:3072
	ds_read_b128 v[178:181], v194
	ds_read_b128 v[182:185], v194 offset:1024
	ds_read_b128 v[186:189], v194 offset:2048
	ds_read_b128 v[194:197], v194 offset:3072
	s_add_i32 m0, s59, 0xc000
	ds_read_b128 v[198:201], v193
	ds_read_b128 v[202:205], v193 offset:1024
	ds_read_b128 v[210:213], v193 offset:2048
	ds_read_b128 v[214:217], v193 offset:3072
	ds_read_b128 v[226:229], v193 offset:4096
	ds_read_b128 v[230:233], v193 offset:5120
	ds_read_b128 v[234:237], v193 offset:6144
	ds_read_b128 v[238:241], v193 offset:7168
	global_load_lds_dwordx4 v154, s[6:7]
	s_add_i32 m0, s59, 0xe000
	s_nop 0
	global_load_lds_dwordx4 v156, s[6:7]
	s_waitcnt vmcnt(8)
	s_waitcnt lgkmcnt(0)
	s_barrier
	s_setprio 1
	s_waitcnt lgkmcnt(0)
	v_mfma_f32_16x16x32_bf16 v[130:133], v[2:5], v[198:201], v[130:133]
	v_mfma_f32_16x16x32_bf16 v[134:137], v[138:141], v[198:201], v[134:137]
	v_mfma_f32_16x16x32_bf16 v[114:117], v[2:5], v[210:213], v[114:117]
	v_mfma_f32_16x16x32_bf16 v[118:121], v[138:141], v[210:213], v[118:121]
	v_mfma_f32_16x16x32_bf16 v[98:101], v[2:5], v[226:229], v[98:101]
	v_mfma_f32_16x16x32_bf16 v[102:105], v[138:141], v[226:229], v[102:105]
	v_mfma_f32_16x16x32_bf16 v[82:85], v[2:5], v[234:237], v[82:85]
	v_mfma_f32_16x16x32_bf16 v[86:89], v[138:141], v[234:237], v[86:89]
	v_mfma_f32_16x16x32_bf16 v[130:133], v[6:9], v[202:205], v[130:133]
	v_mfma_f32_16x16x32_bf16 v[134:137], v[158:161], v[202:205], v[134:137]
	v_mfma_f32_16x16x32_bf16 v[114:117], v[6:9], v[214:217], v[114:117]
	v_mfma_f32_16x16x32_bf16 v[118:121], v[158:161], v[214:217], v[118:121]
	v_mfma_f32_16x16x32_bf16 v[98:101], v[6:9], v[230:233], v[98:101]
	v_mfma_f32_16x16x32_bf16 v[102:105], v[158:161], v[230:233], v[102:105]
	v_mfma_f32_16x16x32_bf16 v[82:85], v[6:9], v[238:241], v[82:85]
	v_mfma_f32_16x16x32_bf16 v[86:89], v[158:161], v[238:241], v[86:89]
	s_setprio 0
	s_setprio 1
	v_mfma_f32_16x16x32_bf16 v[126:129], v[178:181], v[198:201], v[126:129]
	v_mfma_f32_16x16x32_bf16 v[122:125], v[186:189], v[198:201], v[122:125]
	v_mfma_f32_16x16x32_bf16 v[110:113], v[178:181], v[210:213], v[110:113]
	v_mfma_f32_16x16x32_bf16 v[106:109], v[186:189], v[210:213], v[106:109]
	v_mfma_f32_16x16x32_bf16 v[94:97], v[178:181], v[226:229], v[94:97]
	v_mfma_f32_16x16x32_bf16 v[90:93], v[186:189], v[226:229], v[90:93]
	v_mfma_f32_16x16x32_bf16 v[78:81], v[178:181], v[234:237], v[78:81]
	v_mfma_f32_16x16x32_bf16 v[74:77], v[186:189], v[234:237], v[74:77]
	v_mfma_f32_16x16x32_bf16 v[126:129], v[182:185], v[202:205], v[126:129]
	v_mfma_f32_16x16x32_bf16 v[122:125], v[194:197], v[202:205], v[122:125]
	v_mfma_f32_16x16x32_bf16 v[110:113], v[182:185], v[214:217], v[110:113]
	v_mfma_f32_16x16x32_bf16 v[106:109], v[194:197], v[214:217], v[106:109]
	v_mfma_f32_16x16x32_bf16 v[94:97], v[182:185], v[230:233], v[94:97]
	v_mfma_f32_16x16x32_bf16 v[90:93], v[194:197], v[230:233], v[90:93]
	v_mfma_f32_16x16x32_bf16 v[78:81], v[182:185], v[238:241], v[78:81]
	v_mfma_f32_16x16x32_bf16 v[74:77], v[194:197], v[238:241], v[74:77]
	s_setprio 0
	s_barrier
	s_add_i32 s26, s28, s18
	s_mov_b32 m0, s26
	ds_read_b128 v[198:201], v193 offset:16384
	ds_read_b128 v[202:205], v193 offset:17408
	ds_read_b128 v[210:213], v193 offset:18432
	ds_read_b128 v[214:217], v193 offset:19456
	ds_read_b128 v[226:229], v193 offset:20480
	ds_read_b128 v[230:233], v193 offset:21504
	ds_read_b128 v[234:237], v193 offset:22528
	ds_read_b128 v[238:241], v193 offset:23552
	global_load_lds_dwordx4 v146, s[90:91]
	s_add_i32 m0, s26, 0x2000
	s_add_u32 s26, s90, 0x40000
	s_addc_u32 s27, s91, 0
	s_add_i32 s28, s29, s18
	global_load_lds_dwordx4 v142, s[90:91]
	s_mov_b32 m0, s28
	s_nop 0
	global_load_lds_dwordx4 v146, s[26:27]
	s_add_i32 m0, s28, 0x2000
	s_nop 0
	global_load_lds_dwordx4 v142, s[26:27]
	s_mov_b32 m0, s59
	s_nop 0
	global_load_lds_dwordx4 v148, s[92:93]
	s_mov_b32 m0, s62
	s_nop 0
	global_load_lds_dwordx4 v144, s[92:93]
	s_waitcnt vmcnt(8)
	s_waitcnt lgkmcnt(0)
	s_barrier
	s_setprio 1
	s_waitcnt lgkmcnt(0)
	v_mfma_f32_16x16x32_bf16 v[66:69], v[2:5], v[198:201], v[66:69]
	v_mfma_f32_16x16x32_bf16 v[70:73], v[138:141], v[198:201], v[70:73]
	v_mfma_f32_16x16x32_bf16 v[50:53], v[2:5], v[210:213], v[50:53]
	v_mfma_f32_16x16x32_bf16 v[54:57], v[138:141], v[210:213], v[54:57]
	v_mfma_f32_16x16x32_bf16 v[34:37], v[2:5], v[226:229], v[34:37]
	v_mfma_f32_16x16x32_bf16 v[38:41], v[138:141], v[226:229], v[38:41]
	v_mfma_f32_16x16x32_bf16 v[2:5], v[2:5], v[234:237], v[18:21]
	v_mfma_f32_16x16x32_bf16 v[66:69], v[6:9], v[202:205], v[66:69]
	v_mfma_f32_16x16x32_bf16 v[70:73], v[158:161], v[202:205], v[70:73]
	v_mfma_f32_16x16x32_bf16 v[50:53], v[6:9], v[214:217], v[50:53]
	v_mfma_f32_16x16x32_bf16 v[54:57], v[158:161], v[214:217], v[54:57]
	v_mfma_f32_16x16x32_bf16 v[34:37], v[6:9], v[230:233], v[34:37]
	v_mfma_f32_16x16x32_bf16 v[38:41], v[158:161], v[230:233], v[38:41]
	v_mfma_f32_16x16x32_bf16 v[2:5], v[6:9], v[238:241], v[2:5]
	v_mfma_f32_16x16x32_bf16 v[6:9], v[138:141], v[234:237], v[22:25]
	v_mfma_f32_16x16x32_bf16 v[6:9], v[158:161], v[238:241], v[6:9]
	s_setprio 0
	s_setprio 1
	v_mfma_f32_16x16x32_bf16 v[18:21], v[178:181], v[198:201], v[62:65]
	v_mfma_f32_16x16x32_bf16 v[62:65], v[182:185], v[202:205], v[18:21]
	v_mfma_f32_16x16x32_bf16 v[18:21], v[186:189], v[198:201], v[58:61]
	v_mfma_f32_16x16x32_bf16 v[58:61], v[194:197], v[202:205], v[18:21]
	v_mfma_f32_16x16x32_bf16 v[18:21], v[178:181], v[210:213], v[46:49]
	v_mfma_f32_16x16x32_bf16 v[46:49], v[182:185], v[214:217], v[18:21]
	v_mfma_f32_16x16x32_bf16 v[18:21], v[186:189], v[210:213], v[42:45]
	v_mfma_f32_16x16x32_bf16 v[42:45], v[194:197], v[214:217], v[18:21]
	v_mfma_f32_16x16x32_bf16 v[18:21], v[178:181], v[226:229], v[30:33]
	v_mfma_f32_16x16x32_bf16 v[30:33], v[182:185], v[230:233], v[18:21]
	v_mfma_f32_16x16x32_bf16 v[18:21], v[186:189], v[226:229], v[26:29]
	v_mfma_f32_16x16x32_bf16 v[14:17], v[178:181], v[234:237], v[14:17]
	v_mfma_f32_16x16x32_bf16 v[10:13], v[186:189], v[234:237], v[10:13]
	v_mfma_f32_16x16x32_bf16 v[26:29], v[194:197], v[230:233], v[18:21]
	v_mfma_f32_16x16x32_bf16 v[14:17], v[182:185], v[238:241], v[14:17]
	v_mfma_f32_16x16x32_bf16 v[10:13], v[194:197], v[238:241], v[10:13]
	s_setprio 0
	s_barrier
; #define PG8_STAGE(bufoff, gbase, voff) do { _Pragma("unroll") for (int _i = 0; _i < 2; ++_i) \
;         __builtin_amdgcn_global_load_lds((const unsigned*)((const char*)(gbase) + (voff)[_i]), (PG8_LAS unsigned*)(lds + (bufoff) + ldsw + _i * 8192), 16, 0, 0); } while (0)
; #define PG8_LDA(dst, b, h) do { _Pragma("unroll") for (int m = 0; m < 4; ++m) _Pragma("unroll") for (int k = 0; k < 2; ++k) dst[m][k] = *(const PG8_LAS bf16x8*)(lds + PG8_SA(b, h) + aoff + m * 2048 + k * 1024); } while (0)
; #define PG8_LDB(dst, b, h) do { _Pragma("unroll") for (int n = 0; n < 2; ++n) _Pragma("unroll") for (int k = 0; k < 2; ++k) dst[n][k] = *(const PG8_LAS bf16x8*)(lds + PG8_SB(b, h) + boff + n * 2048 + k * 1024); } while (0)
; #define PG8_MMA(ai, bj, At, Bt) do { __builtin_amdgcn_s_setprio(1); _Pragma("unroll") for (int m = 0; m < 4; ++m) _Pragma("unroll") for (int n = 0; n < 2; ++n) _Pragma("unroll") for (int k = 0; k < 2; ++k) \
;         acc[ai][bj][m][n] = __builtin_amdgcn_mfma_f32_16x16x32_bf16(Bt[n][k], At[m][k], acc[ai][bj][m][n], 0, 0, 0); __builtin_amdgcn_s_setprio(0); } while (0)
; #define PG8_WAIT_V(n) asm volatile("s_waitcnt vmcnt(" #n ")" ::: "memory")
; #define PG8_WAIT_L(n) asm volatile("s_waitcnt lgkmcnt(" #n ")" ::: "memory")
; #define PG8_BAR __builtin_amdgcn_s_barrier()
; #define PG8_SCHED __builtin_amdgcn_sched_barrier(0)
; template <class Epi, class Sched, bool ALIGN_EPI = false, bool SP2 = false>
; __device__ __forceinline__ void gemm_phase(PG8_LAS unsigned char* lds, const Gemm g, const Sched& S, const Epi& E) {
;     ...
;             PG8_LDB(B0, 1, 0); PG8_LDB(B1, 1, 1); PG8_SCHED; PG8_LDA(At, 1, 0); PG8_STAGE(PG8_SA(0, 1), a2 + hstep, voffA);
;             PG8_WAIT_V(8); PG8_WAIT_L(0); PG8_BAR; PG8_MMA(0, 0, At, B0); PG8_MMA(0, 1, At, B1); PG8_BAR; PG8_SCHED;
;             PG8_LDA(At, 1, 1); PG8_STAGE(PG8_SB(1, 0), b3, voffB); PG8_STAGE(PG8_SB(1, 1), b3 + hstep, voffB); PG8_STAGE(PG8_SA(1, 0), a3, voffA);
;             PG8_WAIT_V(8); PG8_WAIT_L(0); PG8_BAR; PG8_MMA(1, 0, At, B0); PG8_MMA(1, 1, At, B1); PG8_BAR; PG8_SCHED;
	s_add_i32 s28, 0, 0x18000
	s_add_i32 s29, 0, 0x1c000
	v_add_u32_e32 v158, s28, v191
	v_add_u32_e32 v194, s29, v191
	ds_read_b128 v[18:21], v158
	ds_read_b128 v[22:25], v158 offset:1024
	ds_read_b128 v[138:141], v158 offset:2048
	ds_read_b128 v[158:161], v158 offset:3072
	ds_read_b128 v[178:181], v194
	ds_read_b128 v[182:185], v194 offset:1024
	ds_read_b128 v[186:189], v194 offset:2048
	ds_read_b128 v[194:197], v194 offset:3072
	s_add_u32 s26, s92, 0x40000
	s_addc_u32 s27, s93, 0
	s_mov_b32 m0, s63
	ds_read_b128 v[198:201], v193 offset:32768
	ds_read_b128 v[202:205], v193 offset:33792
	ds_read_b128 v[210:213], v193 offset:34816
	ds_read_b128 v[214:217], v193 offset:35840
	ds_read_b128 v[226:229], v193 offset:36864
	ds_read_b128 v[230:233], v193 offset:37888
	ds_read_b128 v[234:237], v193 offset:38912
	ds_read_b128 v[238:241], v193 offset:39936
	global_load_lds_dwordx4 v148, s[26:27]
	s_mov_b32 m0, s64
	s_nop 0
	global_load_lds_dwordx4 v144, s[26:27]
	s_waitcnt vmcnt(8)
	s_waitcnt lgkmcnt(0)
	s_barrier
	s_setprio 1
	s_waitcnt lgkmcnt(0)
	v_mfma_f32_16x16x32_bf16 v[130:133], v[18:21], v[198:201], v[130:133]
	v_mfma_f32_16x16x32_bf16 v[134:137], v[138:141], v[198:201], v[134:137]
	v_mfma_f32_16x16x32_bf16 v[114:117], v[18:21], v[210:213], v[114:117]
	v_mfma_f32_16x16x32_bf16 v[118:121], v[138:141], v[210:213], v[118:121]
	v_mfma_f32_16x16x32_bf16 v[98:101], v[18:21], v[226:229], v[98:101]
	v_mfma_f32_16x16x32_bf16 v[102:105], v[138:141], v[226:229], v[102:105]
	v_mfma_f32_16x16x32_bf16 v[82:85], v[18:21], v[234:237], v[82:85]
	v_mfma_f32_16x16x32_bf16 v[86:89], v[138:141], v[234:237], v[86:89]
	v_mfma_f32_16x16x32_bf16 v[130:133], v[22:25], v[202:205], v[130:133]
	v_mfma_f32_16x16x32_bf16 v[134:137], v[158:161], v[202:205], v[134:137]
	v_mfma_f32_16x16x32_bf16 v[114:117], v[22:25], v[214:217], v[114:117]
	v_mfma_f32_16x16x32_bf16 v[118:121], v[158:161], v[214:217], v[118:121]
	v_mfma_f32_16x16x32_bf16 v[98:101], v[22:25], v[230:233], v[98:101]
	v_mfma_f32_16x16x32_bf16 v[102:105], v[158:161], v[230:233], v[102:105]
	v_mfma_f32_16x16x32_bf16 v[82:85], v[22:25], v[238:241], v[82:85]
	v_mfma_f32_16x16x32_bf16 v[86:89], v[158:161], v[238:241], v[86:89]
	s_setprio 0
	s_setprio 1
	v_mfma_f32_16x16x32_bf16 v[126:129], v[178:181], v[198:201], v[126:129]
	v_mfma_f32_16x16x32_bf16 v[122:125], v[186:189], v[198:201], v[122:125]
	v_mfma_f32_16x16x32_bf16 v[110:113], v[178:181], v[210:213], v[110:113]
	v_mfma_f32_16x16x32_bf16 v[106:109], v[186:189], v[210:213], v[106:109]
	v_mfma_f32_16x16x32_bf16 v[94:97], v[178:181], v[226:229], v[94:97]
	v_mfma_f32_16x16x32_bf16 v[90:93], v[186:189], v[226:229], v[90:93]
	v_mfma_f32_16x16x32_bf16 v[78:81], v[178:181], v[234:237], v[78:81]
	v_mfma_f32_16x16x32_bf16 v[74:77], v[186:189], v[234:237], v[74:77]
	v_mfma_f32_16x16x32_bf16 v[126:129], v[182:185], v[202:205], v[126:129]
	v_mfma_f32_16x16x32_bf16 v[122:125], v[194:197], v[202:205], v[122:125]
	v_mfma_f32_16x16x32_bf16 v[110:113], v[182:185], v[214:217], v[110:113]
	v_mfma_f32_16x16x32_bf16 v[106:109], v[194:197], v[214:217], v[106:109]
	v_mfma_f32_16x16x32_bf16 v[94:97], v[182:185], v[230:233], v[94:97]
	v_mfma_f32_16x16x32_bf16 v[90:93], v[194:197], v[230:233], v[90:93]
	v_mfma_f32_16x16x32_bf16 v[78:81], v[182:185], v[238:241], v[78:81]
	v_mfma_f32_16x16x32_bf16 v[74:77], v[194:197], v[238:241], v[74:77]
	s_setprio 0
	s_barrier
	s_add_i32 s26, s28, s18
	s_mov_b32 m0, s26
	ds_read_b128 v[198:201], v193 offset:49152
	ds_read_b128 v[202:205], v193 offset:50176
	ds_read_b128 v[210:213], v193 offset:51200
	ds_read_b128 v[214:217], v193 offset:52224
	ds_read_b128 v[226:229], v193 offset:53248
	ds_read_b128 v[230:233], v193 offset:54272
	ds_read_b128 v[234:237], v193 offset:55296
	ds_read_b128 v[238:241], v193 offset:56320
	s_add_u32 s100, s90, 0x80
	s_addc_u32 s101, s91, 0
	global_load_lds_dwordx4 v146, s[100:101]
	s_add_i32 m0, s26, 0x2000
	s_add_u32 s26, s90, 0x40080
	s_addc_u32 s27, s91, 0
	s_add_i32 s28, s29, s18
	s_add_u32 s100, s90, 0x80
	s_addc_u32 s101, s91, 0
	global_load_lds_dwordx4 v142, s[100:101]
	s_mov_b32 m0, s28
	s_nop 0
	global_load_lds_dwordx4 v146, s[26:27]
	s_add_i32 m0, s28, 0x2000
	s_nop 0
	global_load_lds_dwordx4 v142, s[26:27]
	s_mov_b32 m0, s37
	s_nop 0
	s_add_u32 s100, s92, 0x80
	s_addc_u32 s101, s93, 0
	global_load_lds_dwordx4 v148, s[100:101]
	s_mov_b32 m0, s38
	s_nop 0
	s_add_u32 s100, s92, 0x80
	s_addc_u32 s101, s93, 0
	global_load_lds_dwordx4 v144, s[100:101]
	s_waitcnt vmcnt(8)
	s_waitcnt lgkmcnt(0)
	s_barrier
	s_setprio 1
	s_waitcnt lgkmcnt(0)
	v_mfma_f32_16x16x32_bf16 v[2:5], v[18:21], v[234:237], v[2:5]
	v_mfma_f32_16x16x32_bf16 v[66:69], v[18:21], v[198:201], v[66:69]
	v_mfma_f32_16x16x32_bf16 v[70:73], v[138:141], v[198:201], v[70:73]
	v_mfma_f32_16x16x32_bf16 v[50:53], v[18:21], v[210:213], v[50:53]
	v_mfma_f32_16x16x32_bf16 v[54:57], v[138:141], v[210:213], v[54:57]
	v_mfma_f32_16x16x32_bf16 v[34:37], v[18:21], v[226:229], v[34:37]
	v_mfma_f32_16x16x32_bf16 v[38:41], v[138:141], v[226:229], v[38:41]
	v_mfma_f32_16x16x32_bf16 v[18:21], v[22:25], v[238:241], v[2:5]
	v_mfma_f32_16x16x32_bf16 v[2:5], v[138:141], v[234:237], v[6:9]
	v_mfma_f32_16x16x32_bf16 v[66:69], v[22:25], v[202:205], v[66:69]
	v_mfma_f32_16x16x32_bf16 v[70:73], v[158:161], v[202:205], v[70:73]
	v_mfma_f32_16x16x32_bf16 v[50:53], v[22:25], v[214:217], v[50:53]
	v_mfma_f32_16x16x32_bf16 v[54:57], v[158:161], v[214:217], v[54:57]
	v_mfma_f32_16x16x32_bf16 v[34:37], v[22:25], v[230:233], v[34:37]
	v_mfma_f32_16x16x32_bf16 v[38:41], v[158:161], v[230:233], v[38:41]
	v_mfma_f32_16x16x32_bf16 v[22:25], v[158:161], v[238:241], v[2:5]
	s_setprio 0
	s_setprio 1
	v_mfma_f32_16x16x32_bf16 v[2:5], v[178:181], v[198:201], v[62:65]
	v_mfma_f32_16x16x32_bf16 v[62:65], v[182:185], v[202:205], v[2:5]
	v_mfma_f32_16x16x32_bf16 v[2:5], v[186:189], v[198:201], v[58:61]
	v_mfma_f32_16x16x32_bf16 v[58:61], v[194:197], v[202:205], v[2:5]
	v_mfma_f32_16x16x32_bf16 v[2:5], v[178:181], v[210:213], v[46:49]
	v_mfma_f32_16x16x32_bf16 v[46:49], v[182:185], v[214:217], v[2:5]
	v_mfma_f32_16x16x32_bf16 v[2:5], v[186:189], v[210:213], v[42:45]
	v_mfma_f32_16x16x32_bf16 v[42:45], v[194:197], v[214:217], v[2:5]
	v_mfma_f32_16x16x32_bf16 v[2:5], v[178:181], v[226:229], v[30:33]
	v_mfma_f32_16x16x32_bf16 v[30:33], v[182:185], v[230:233], v[2:5]
	v_mfma_f32_16x16x32_bf16 v[2:5], v[186:189], v[226:229], v[26:29]
	v_mfma_f32_16x16x32_bf16 v[26:29], v[194:197], v[230:233], v[2:5]
	v_mfma_f32_16x16x32_bf16 v[2:5], v[178:181], v[234:237], v[14:17]
	v_mfma_f32_16x16x32_bf16 v[14:17], v[182:185], v[238:241], v[2:5]
	v_mfma_f32_16x16x32_bf16 v[2:5], v[186:189], v[234:237], v[10:13]
	v_mfma_f32_16x16x32_bf16 v[10:13], v[194:197], v[238:241], v[2:5]
	s_setprio 0
	s_barrier
	s_add_i32 s96, s96, 2
	s_add_u32 s6, s6, 0x100
	s_addc_u32 s7, s7, 0
	s_add_u32 s94, s94, 0x100
	s_addc_u32 s95, s95, 0
	s_cmp_gt_u32 s96, 13
	s_cbranch_scc0 .LBB0_340
	s_and_b64 vcc, exec, s[80:81]
	s_cbranch_vccz .LBB0_343
	s_barrier

; __device__ __forceinline__ unsigned pk2(float lo, float hi) { const f32x2 v = {lo, hi}; return __builtin_bit_cast(unsigned, __builtin_convertvector(v, bf16x2_t)); }
; __device__ __forceinline__ float bflo(unsigned w) { return __uint_as_float(w << 16); }
; __device__ __forceinline__ float bfhi(unsigned w) { return __uint_as_float(w & 0xffff0000u); }
; #define LDS_FENCE() asm volatile("s_waitcnt lgkmcnt(0)" ::: "memory")
; __device__ __forceinline__ int crow(int r, int hi) { return (r & 3) + 8 * (r >> 2) + 4 * hi; }
; template <bool BWD, int MODE  >
; __device__ __forceinline__ void ssm_pass(const bf16* proj, int rowbase, int g, const bf16x8* BBp, const bf16x8* CCp, float ar, float ai, float& sr, float& si,
;                                          LAS unsigned* XS, int lane, f32x4* ysc, const float* Dp, bf16* zbuf) {
;     ...
;         const f32x16 x0 = __builtin_amdgcn_mfma_f32_32x32x16_bf16(ucur, bb[0], z16, 0, 0, 0);
;         const f32x16 x1 = __builtin_amdgcn_mfma_f32_32x32x16_bf16(ucur, bb[1], z16, 0, 0, 0);
;         const f32x16 x2 = __builtin_amdgcn_mfma_f32_32x32x16_bf16(ucur, bb[2], z16, 0, 0, 0);
;         const f32x16 x3 = __builtin_amdgcn_mfma_f32_32x32x16_bf16(ucur, bb[3], z16, 0, 0, 0);
; #pragma unroll
;         for (int r = 0; r < 16; ++r) { const int t = crow(r, hi); XS[t * XS_STRIDE + ql] = pk2(x0[r], x2[r]); XS[t * XS_STRIDE + 32 + ql] = pk2(x1[r], x3[r]); }
;         LDS_FENCE();
; #pragma unroll
;         for (int tt = 0; tt < 32; ++tt) {
;             const int t = BWD ? 31 - tt : tt;
;             const unsigned v = XS[t * XS_STRIDE + lane];
;             const float nr = fmaf(ar, sr, fmaf(-ai, si, bflo(v))), ni = fmaf(ar, si, fmaf(ai, sr, bfhi(v)));
;             sr = nr; si = ni;
;             if (MODE > 0) XS[t * XS_STRIDE + lane] = pk2(sr, si);
;         }
.LBB0_510:
	v_mfma_f32_32x32x16_bf16 v[2:17], v[50:53], v[82:85], 0
	v_add_u32_e32 v125, 0x4000, v160
	v_add_u32_e32 v179, 0x4800, v160
	v_add_u32_e32 v180, 0x4a00, v160
	v_add_u32_e32 v181, 0x5000, v160
	v_add_u32_e32 v182, 0x5400, v160
	v_add_u32_e32 v183, 0x5800, v160
	v_add_u32_e32 v184, 0x5a00, v160
	v_mfma_f32_32x32x16_bf16 v[18:33], v[50:53], v[66:69], 0
	v_add_u32_e32 v185, 0x5c00, v160
	v_add_u32_e32 v186, 0x5e00, v158
	v_add_u32_e32 v187, 0x5c00, v158
	v_add_u32_e32 v188, 0x5a00, v158
	v_add_u32_e32 v189, 0x5800, v158
	v_add_u32_e32 v190, 0x5600, v158
	v_add_u32_e32 v191, 0x5400, v158
	v_mfma_f32_32x32x16_bf16 v[34:49], v[50:53], v[70:73], 0
	v_add_u32_e32 v192, 0x5200, v158
	v_add_u32_e32 v193, 0x5000, v158
	v_add_u32_e32 v194, 0x4c00, v158
	v_add_u32_e32 v195, 0x4800, v158
	v_add_u32_e32 v196, 0x4400, v158
	v_add_u32_e32 v197, 0x4000, v158
	s_mov_b32 s28, 0x19007000
	v_mfma_f32_32x32x16_bf16 v[50:65], v[50:53], v[86:89], 0
	s_add_i32 s36, s36, -1
	v_lshl_add_u64 v[130:131], v[130:131], 0, s[68:69]
	v_add_u32_e32 v235, 1088, v197
	v_add_u32_e32 v236, 2176, v197
	v_add_u32_e32 v237, 3264, v197
	v_add_u32_e32 v238, 4352, v197
	v_add_u32_e32 v239, 5440, v197
	v_add_u32_e32 v240, 6528, v197
	v_add_u32_e32 v241, 7616, v197
	s_nop 1
	v_permlane32_swap_b32_e32 v17, v33
	v_permlane32_swap_b32_e32 v16, v32
	v_permlane32_swap_b32_e32 v15, v31
	v_permlane32_swap_b32_e32 v14, v30
	v_permlane32_swap_b32_e32 v13, v29
	v_permlane32_swap_b32_e32 v12, v28
	v_permlane32_swap_b32_e32 v11, v27
	v_permlane32_swap_b32_e32 v10, v26
	v_permlane32_swap_b32_e32 v9, v25
	v_permlane32_swap_b32_e32 v8, v24
	v_permlane32_swap_b32_e32 v7, v23
	v_permlane32_swap_b32_e32 v6, v22
	v_permlane32_swap_b32_e32 v5, v21
	v_permlane32_swap_b32_e32 v4, v20
	v_permlane32_swap_b32_e32 v3, v19
	v_permlane32_swap_b32_e32 v2, v18
	v_permlane32_swap_b32_e32 v49, v65
	v_permlane32_swap_b32_e32 v48, v64
	v_permlane32_swap_b32_e32 v47, v63
	v_permlane32_swap_b32_e32 v46, v62
	v_permlane32_swap_b32_e32 v45, v61
	v_permlane32_swap_b32_e32 v44, v60
	v_permlane32_swap_b32_e32 v43, v59
	v_permlane32_swap_b32_e32 v42, v58
	v_permlane32_swap_b32_e32 v41, v57
	v_permlane32_swap_b32_e32 v40, v56
	v_permlane32_swap_b32_e32 v39, v55
	v_permlane32_swap_b32_e32 v38, v54
	v_permlane32_swap_b32_e32 v37, v53
	v_permlane32_swap_b32_e32 v36, v52
	v_permlane32_swap_b32_e32 v35, v51
	v_permlane32_swap_b32_e32 v34, v50
	v_fmac_f32_e32 v33, v126, v133
	v_fmac_f32_e32 v65, v103, v132
	v_fmac_f32_e32 v33, v102, v132
	v_fmac_f32_e32 v65, v102, v133
	v_fmac_f32_e32 v32, v126, v65
	v_fmac_f32_e32 v64, v103, v33
	v_fmac_f32_e32 v32, v102, v33
	v_fmac_f32_e32 v64, v102, v65
	v_cvt_pk_bf16_f32 v242, v33, v65
	v_cvt_pk_bf16_f32 v243, v32, v64
	ds_write2_b32 v241, v242, v243 offset0:204 offset1:136
	v_fmac_f32_e32 v31, v126, v64
	v_fmac_f32_e32 v63, v103, v32
	v_fmac_f32_e32 v31, v102, v32
	v_fmac_f32_e32 v63, v102, v64
	v_fmac_f32_e32 v30, v126, v63
	v_fmac_f32_e32 v62, v103, v31
	v_fmac_f32_e32 v30, v102, v31
	v_fmac_f32_e32 v62, v102, v63
	v_cvt_pk_bf16_f32 v244, v31, v63
	v_cvt_pk_bf16_f32 v245, v30, v62
	ds_write2_b32 v241, v244, v245 offset0:68 offset1:0
	v_fmac_f32_e32 v17, v126, v62
	v_fmac_f32_e32 v49, v103, v30
	v_fmac_f32_e32 v17, v102, v30
	v_fmac_f32_e32 v49, v102, v62
	v_fmac_f32_e32 v16, v126, v49
	v_fmac_f32_e32 v48, v103, v17
	v_fmac_f32_e32 v16, v102, v17
	v_fmac_f32_e32 v48, v102, v49
	v_cvt_pk_bf16_f32 v242, v17, v49
	v_cvt_pk_bf16_f32 v243, v16, v48
	ds_write2_b32 v240, v242, v243 offset0:204 offset1:136
	v_fmac_f32_e32 v15, v126, v48
	v_fmac_f32_e32 v47, v103, v16
	v_fmac_f32_e32 v15, v102, v16
	v_fmac_f32_e32 v47, v102, v48
	v_fmac_f32_e32 v14, v126, v47
	v_fmac_f32_e32 v46, v103, v15
	v_fmac_f32_e32 v14, v102, v15
	v_fmac_f32_e32 v46, v102, v47
	v_cvt_pk_bf16_f32 v244, v15, v47
	v_cvt_pk_bf16_f32 v245, v14, v46
	ds_write2_b32 v240, v244, v245 offset0:68 offset1:0
	v_fmac_f32_e32 v29, v126, v46
	v_fmac_f32_e32 v61, v103, v14
	v_fmac_f32_e32 v29, v102, v14
	v_fmac_f32_e32 v61, v102, v46
	v_fmac_f32_e32 v28, v126, v61
	v_fmac_f32_e32 v60, v103, v29
	v_fmac_f32_e32 v28, v102, v29
	v_fmac_f32_e32 v60, v102, v61
	v_cvt_pk_bf16_f32 v242, v29, v61
	v_cvt_pk_bf16_f32 v243, v28, v60
	ds_write2_b32 v239, v242, v243 offset0:204 offset1:136
	v_fmac_f32_e32 v27, v126, v60
	v_fmac_f32_e32 v59, v103, v28
	v_fmac_f32_e32 v27, v102, v28
	v_fmac_f32_e32 v59, v102, v60
	v_fmac_f32_e32 v26, v126, v59
	v_fmac_f32_e32 v58, v103, v27
	v_fmac_f32_e32 v26, v102, v27
	v_fmac_f32_e32 v58, v102, v59
	v_cvt_pk_bf16_f32 v244, v27, v59
	v_cvt_pk_bf16_f32 v245, v26, v58
	ds_write2_b32 v239, v244, v245 offset0:68 offset1:0
	v_fmac_f32_e32 v13, v126, v58
	v_fmac_f32_e32 v45, v103, v26
	v_fmac_f32_e32 v13, v102, v26
	v_fmac_f32_e32 v45, v102, v58
	v_fmac_f32_e32 v12, v126, v45
	v_fmac_f32_e32 v44, v103, v13
	v_fmac_f32_e32 v12, v102, v13
	v_fmac_f32_e32 v44, v102, v45
	v_cvt_pk_bf16_f32 v242, v13, v45
; #define LAS __attribute__((address_space(3)))
; __device__ __forceinline__ unsigned pk2(float lo, float hi) { const f32x2 v = {lo, hi}; return __builtin_bit_cast(unsigned, __builtin_convertvector(v, bf16x2_t)); }
; __device__ __forceinline__ float bflo(unsigned w) { return __uint_as_float(w << 16); }
; __device__ __forceinline__ float bfhi(unsigned w) { return __uint_as_float(w & 0xffff0000u); }
; #define LDS_FENCE() asm volatile("s_waitcnt lgkmcnt(0)" ::: "memory")
; template <bool BWD, int MODE  >
; __device__ __forceinline__ void ssm_pass(const bf16* proj, int rowbase, int g, const bf16x8* BBp, const bf16x8* CCp, float ar, float ai, float& sr, float& si,
;                                          LAS unsigned* XS, int lane, f32x4* ysc, const float* Dp, bf16* zbuf) {
;     ...
;         for (int tt = 0; tt < 32; ++tt) {
;             const int t = BWD ? 31 - tt : tt;
;             const unsigned v = XS[t * XS_STRIDE + lane];
;             const float nr = fmaf(ar, sr, fmaf(-ai, si, bflo(v))), ni = fmaf(ar, si, fmaf(ai, sr, bfhi(v)));
;             sr = nr; si = ni;
;             if (MODE > 0) XS[t * XS_STRIDE + lane] = pk2(sr, si);
;         }
;         if (MODE > 0) {
;             LDS_FENCE();
;             const LAS unsigned char* ab = (const LAS unsigned char*)XS + (lane & 15) * (XS_STRIDE * 4) + (lane >> 4) * 16;
; #pragma unroll
;             for (int kk = 0; kk < 4; ++kk) {
;                 const bf16x8 a0 = *(const LAS bf16x8*)(ab + kk * 64), a1 = *(const LAS bf16x8*)(ab + 16 * XS_STRIDE * 4 + kk * 64);
;                 y0 = __builtin_amdgcn_mfma_f32_16x16x32_bf16(a0, cc[kk], y0, 0, 0, 0);
;                 y1 = __builtin_amdgcn_mfma_f32_16x16x32_bf16(a1, cc[kk], y1, 0, 0, 0);
;             }
;             if (MODE == 1) { ysc[(ch * 2 + 0) * 64 + lane] = y0; ysc[(ch * 2 + 1) * 64 + lane] = y1; }
	v_cvt_pk_bf16_f32 v243, v12, v44
	ds_write2_b32 v238, v242, v243 offset0:204 offset1:136
	v_fmac_f32_e32 v11, v126, v44
	v_fmac_f32_e32 v43, v103, v12
	v_fmac_f32_e32 v11, v102, v12
	v_fmac_f32_e32 v43, v102, v44
	v_fmac_f32_e32 v10, v126, v43
	v_fmac_f32_e32 v42, v103, v11
	v_fmac_f32_e32 v10, v102, v11
	v_fmac_f32_e32 v42, v102, v43
	v_cvt_pk_bf16_f32 v244, v11, v43
	v_cvt_pk_bf16_f32 v245, v10, v42
	ds_write2_b32 v238, v244, v245 offset0:68 offset1:0
	v_fmac_f32_e32 v25, v126, v42
	v_fmac_f32_e32 v57, v103, v10
	v_fmac_f32_e32 v25, v102, v10
	v_fmac_f32_e32 v57, v102, v42
	v_fmac_f32_e32 v24, v126, v57
	v_fmac_f32_e32 v56, v103, v25
	v_fmac_f32_e32 v24, v102, v25
	v_fmac_f32_e32 v56, v102, v57
	v_cvt_pk_bf16_f32 v242, v25, v57
	v_cvt_pk_bf16_f32 v243, v24, v56
	ds_write2_b32 v237, v242, v243 offset0:204 offset1:136
	v_fmac_f32_e32 v23, v126, v56
	v_fmac_f32_e32 v55, v103, v24
	v_fmac_f32_e32 v23, v102, v24
	v_fmac_f32_e32 v55, v102, v56
	v_fmac_f32_e32 v22, v126, v55
	v_fmac_f32_e32 v54, v103, v23
	v_fmac_f32_e32 v22, v102, v23
	v_fmac_f32_e32 v54, v102, v55
	v_cvt_pk_bf16_f32 v244, v23, v55
	v_cvt_pk_bf16_f32 v245, v22, v54
	ds_write2_b32 v237, v244, v245 offset0:68 offset1:0
	v_fmac_f32_e32 v9, v126, v54
	v_fmac_f32_e32 v41, v103, v22
	v_fmac_f32_e32 v9, v102, v22
	v_fmac_f32_e32 v41, v102, v54
	v_fmac_f32_e32 v8, v126, v41
	v_fmac_f32_e32 v40, v103, v9
	v_fmac_f32_e32 v8, v102, v9
	v_fmac_f32_e32 v40, v102, v41
	v_cvt_pk_bf16_f32 v242, v9, v41
	v_cvt_pk_bf16_f32 v243, v8, v40
	ds_write2_b32 v236, v242, v243 offset0:204 offset1:136
	v_fmac_f32_e32 v7, v126, v40
	v_fmac_f32_e32 v39, v103, v8
	v_fmac_f32_e32 v7, v102, v8
	v_fmac_f32_e32 v39, v102, v40
	v_fmac_f32_e32 v6, v126, v39
	v_fmac_f32_e32 v38, v103, v7
	v_fmac_f32_e32 v6, v102, v7
	v_fmac_f32_e32 v38, v102, v39
	v_cvt_pk_bf16_f32 v244, v7, v39
	v_cvt_pk_bf16_f32 v245, v6, v38
	ds_write2_b32 v236, v244, v245 offset0:68 offset1:0
	v_fmac_f32_e32 v21, v126, v38
	v_fmac_f32_e32 v53, v103, v6
	v_fmac_f32_e32 v21, v102, v6
	v_fmac_f32_e32 v53, v102, v38
	v_fmac_f32_e32 v20, v126, v53
	v_fmac_f32_e32 v52, v103, v21
	v_fmac_f32_e32 v20, v102, v21
	v_fmac_f32_e32 v52, v102, v53
	v_cvt_pk_bf16_f32 v242, v21, v53
	v_cvt_pk_bf16_f32 v243, v20, v52
	ds_write2_b32 v235, v242, v243 offset0:204 offset1:136
	v_fmac_f32_e32 v19, v126, v52
	v_fmac_f32_e32 v51, v103, v20
	v_fmac_f32_e32 v19, v102, v20
	v_fmac_f32_e32 v51, v102, v52
	v_fmac_f32_e32 v18, v126, v51
	v_fmac_f32_e32 v50, v103, v19
	v_fmac_f32_e32 v18, v102, v19
	v_fmac_f32_e32 v50, v102, v51
	v_cvt_pk_bf16_f32 v244, v19, v51
	v_cvt_pk_bf16_f32 v245, v18, v50
	ds_write2_b32 v235, v244, v245 offset0:68 offset1:0
	v_fmac_f32_e32 v5, v126, v50
	v_fmac_f32_e32 v37, v103, v18
	v_fmac_f32_e32 v5, v102, v18
	v_fmac_f32_e32 v37, v102, v50
	v_fmac_f32_e32 v4, v126, v37
	v_fmac_f32_e32 v36, v103, v5
	v_fmac_f32_e32 v4, v102, v5
	v_fmac_f32_e32 v36, v102, v37
	v_cvt_pk_bf16_f32 v242, v5, v37
	v_cvt_pk_bf16_f32 v243, v4, v36
	ds_write2_b32 v197, v242, v243 offset0:204 offset1:136
	v_fmac_f32_e32 v3, v126, v36
	v_fmac_f32_e32 v35, v103, v4
	v_fmac_f32_e32 v3, v102, v4
	v_fmac_f32_e32 v35, v102, v36
	v_fmac_f32_e32 v2, v126, v35
	v_fmac_f32_e32 v34, v103, v3
	v_fmac_f32_e32 v2, v102, v3
	v_fmac_f32_e32 v34, v102, v35
	v_cvt_pk_bf16_f32 v244, v3, v35
	v_cvt_pk_bf16_f32 v245, v2, v34
	ds_write2_b32 v197, v244, v245 offset0:68 offset1:0
	v_mov_b32_e32 v132, v2
	v_mov_b32_e32 v133, v34
	s_waitcnt vmcnt(0)
	v_mov_b64_e32 v[50:51], v[98:99]
	v_mov_b64_e32 v[52:53], v[100:101]
	s_waitcnt lgkmcnt(0)
	ds_read_b128 v[2:5], v178 offset:16384
	ds_read_b128 v[6:9], v178 offset:16448
	ds_read_b128 v[10:13], v178 offset:20736
	ds_read_b128 v[14:17], v178 offset:20800
	s_waitcnt lgkmcnt(3)
	v_mfma_f32_16x16x32_bf16 v[2:5], v[2:5], v[90:93], 0
	s_waitcnt lgkmcnt(1)
	v_mfma_f32_16x16x32_bf16 v[10:13], v[10:13], v[90:93], 0
	v_mfma_f32_16x16x32_bf16 v[2:5], v[6:9], v[74:77], v[2:5]
	s_waitcnt lgkmcnt(0)
	v_mfma_f32_16x16x32_bf16 v[6:9], v[14:17], v[74:77], v[10:13]
	s_nop 4
	ds_read_b128 v[10:13], v178 offset:16512
	ds_read_b128 v[14:17], v178 offset:16576
	s_waitcnt lgkmcnt(1)
	v_mfma_f32_16x16x32_bf16 v[2:5], v[10:13], v[78:81], v[2:5]
	ds_read_b128 v[10:13], v178 offset:20864
	ds_read_b128 v[18:21], v178 offset:20928
	s_waitcnt lgkmcnt(1)
	v_mfma_f32_16x16x32_bf16 v[6:9], v[10:13], v[78:81], v[6:9]
	v_lshl_add_u64 v[10:11], v[106:107], 0, s[84:85]
	v_add_co_u32_e32 v10, vcc, s28, v10
	v_mfma_f32_16x16x32_bf16 v[2:5], v[14:17], v[94:97], v[2:5]
	s_nop 0
	v_addc_co_u32_e32 v11, vcc, 0, v11, vcc
	s_add_u32 s84, s84, 0xfffff800
	s_waitcnt lgkmcnt(0)
	v_mfma_f32_16x16x32_bf16 v[6:9], v[18:21], v[94:97], v[6:9]
	s_nop 2
	global_store_dwordx4 v[10:11], v[2:5], off offset:2048
	s_nop 3
	global_store_dwordx4 v[10:11], v[6:9], off offset:3072
	s_waitcnt lgkmcnt(0)
	s_addc_u32 s85, s85, -1
	s_cmp_lg_u32 s36, 0
	s_cbranch_scc0 .LBB0_513

; __device__ __forceinline__ unsigned pk2(float lo, float hi) { const f32x2 v = {lo, hi}; return __builtin_bit_cast(unsigned, __builtin_convertvector(v, bf16x2_t)); }
; __device__ __forceinline__ float bflo(unsigned w) { return __uint_as_float(w << 16); }
; __device__ __forceinline__ float bfhi(unsigned w) { return __uint_as_float(w & 0xffff0000u); }
; #define LDS_FENCE() asm volatile("s_waitcnt lgkmcnt(0)" ::: "memory")
; __device__ __forceinline__ int crow(int r, int hi) { return (r & 3) + 8 * (r >> 2) + 4 * hi; }
; template <bool BWD, int MODE  >
; __device__ __forceinline__ void ssm_pass(const bf16* proj, int rowbase, int g, const bf16x8* BBp, const bf16x8* CCp, float ar, float ai, float& sr, float& si,
;                                          LAS unsigned* XS, int lane, f32x4* ysc, const float* Dp, bf16* zbuf) {
;     ...
;         if (c < 15) unext = *(const bf16x8*)(up + (size_t)(BWD ? ch - 1 : ch + 1) * 32 * DIN);
;         f32x4 y0 = (f32x4){0.f, 0.f, 0.f, 0.f}, y1 = y0; bf16 uvl[8];
;         if (MODE == 2) {
;             y0 = ysc[(ch * 2 + 0) * 64 + lane]; y1 = ysc[(ch * 2 + 1) * 64 + lane];
; #pragma unroll
;             for (int q = 0; q < 8; ++q) uvl[q] = proj[(size_t)(rowbase + 32 * ch + 16 * (q >> 2) + 4 * (lane >> 4) + (q & 3)) * DIN + 768 + g * 16 + (lane & 15)];
;         }
;         f32x16 z16;
; #pragma unroll
;         for (int r = 0; r < 16; ++r) z16[r] = 0.f;
;         const f32x16 x0 = __builtin_amdgcn_mfma_f32_32x32x16_bf16(ucur, bb[0], z16, 0, 0, 0);
;         const f32x16 x1 = __builtin_amdgcn_mfma_f32_32x32x16_bf16(ucur, bb[1], z16, 0, 0, 0);
;         const f32x16 x2 = __builtin_amdgcn_mfma_f32_32x32x16_bf16(ucur, bb[2], z16, 0, 0, 0);
;         const f32x16 x3 = __builtin_amdgcn_mfma_f32_32x32x16_bf16(ucur, bb[3], z16, 0, 0, 0);
; #pragma unroll
;         for (int r = 0; r < 16; ++r) { const int t = crow(r, hi); XS[t * XS_STRIDE + ql] = pk2(x0[r], x2[r]); XS[t * XS_STRIDE + 32 + ql] = pk2(x1[r], x3[r]); }
;         LDS_FENCE();
; #pragma unroll
;         for (int tt = 0; tt < 32; ++tt) {
;             const int t = BWD ? 31 - tt : tt;
;             const unsigned v = XS[t * XS_STRIDE + lane];
;             const float nr = fmaf(ar, sr, fmaf(-ai, si, bflo(v))), ni = fmaf(ar, si, fmaf(ai, sr, bfhi(v)));
;             sr = nr; si = ni;
;             if (MODE > 0) XS[t * XS_STRIDE + lane] = pk2(sr, si);
;         }
.LBB0_518:
	v_mfma_f32_32x32x16_bf16 v[2:17], v[50:53], v[82:85], 0
	global_load_dwordx4 v[106:109], v[138:139], off offset:-1024
	global_load_dwordx4 v[102:105], v[138:139], off
	v_add_u32_e32 v150, s26, v198
	v_mad_i64_i32 v[200:201], s[28:29], v150, s44, v[134:135]
	v_add_u32_e32 v154, 1, v150
	v_add_u32_e32 v152, 2, v150
	v_add_u32_e32 v148, 3, v150
	v_mfma_f32_32x32x16_bf16 v[18:33], v[50:53], v[66:69], 0
	v_add_u32_e32 v146, 16, v150
	v_add_u32_e32 v144, 17, v150
	v_add_u32_e32 v142, 18, v150
	v_add_u32_e32 v140, 19, v150
	v_mad_i64_i32 v[202:203], s[28:29], v154, s44, v[134:135]
	v_mad_i64_i32 v[204:205], s[28:29], v152, s44, v[134:135]
	v_mfma_f32_32x32x16_bf16 v[34:49], v[50:53], v[70:73], 0
	v_mad_i64_i32 v[206:207], s[28:29], v148, s44, v[134:135]
	v_mad_i64_i32 v[210:211], s[28:29], v146, s44, v[134:135]
	v_mad_i64_i32 v[212:213], s[28:29], v144, s44, v[134:135]
	v_mad_i64_i32 v[214:215], s[28:29], v142, s44, v[134:135]
	v_mfma_f32_32x32x16_bf16 v[50:65], v[50:53], v[86:89], 0
	v_mad_i64_i32 v[216:217], s[28:29], v140, s44, v[134:135]
	v_ashrrev_i32_e32 v151, 31, v150
	v_ashrrev_i32_e32 v155, 31, v154
	v_ashrrev_i32_e32 v153, 31, v152
	v_ashrrev_i32_e32 v149, 31, v148
	global_load_ushort v226, v[200:201], off offset:1536
	global_load_ushort v227, v[202:203], off offset:1536
	global_load_ushort v228, v[204:205], off offset:1536
	global_load_ushort v229, v[206:207], off offset:1536
	global_load_ushort v230, v[210:211], off offset:1536
	global_load_ushort v231, v[212:213], off offset:1536
	global_load_ushort v232, v[214:215], off offset:1536
	global_load_ushort v233, v[216:217], off offset:1536
	v_ashrrev_i32_e32 v147, 31, v146
	v_ashrrev_i32_e32 v145, 31, v144
	v_ashrrev_i32_e32 v143, 31, v142
	v_ashrrev_i32_e32 v141, 31, v140
	v_add_u32_e32 v235, 1088, v197
	v_add_u32_e32 v236, 2176, v197
	v_add_u32_e32 v237, 3264, v197
	v_add_u32_e32 v238, 4352, v197
	v_add_u32_e32 v239, 5440, v197
	v_add_u32_e32 v240, 6528, v197
	v_add_u32_e32 v241, 7616, v197
	s_nop 1
	v_permlane32_swap_b32_e32 v2, v18
	v_permlane32_swap_b32_e32 v3, v19
	v_permlane32_swap_b32_e32 v4, v20
	v_permlane32_swap_b32_e32 v5, v21
	v_permlane32_swap_b32_e32 v6, v22
	v_permlane32_swap_b32_e32 v7, v23
	v_permlane32_swap_b32_e32 v8, v24
	v_permlane32_swap_b32_e32 v9, v25
	v_permlane32_swap_b32_e32 v10, v26
	v_permlane32_swap_b32_e32 v11, v27
	v_permlane32_swap_b32_e32 v12, v28
	v_permlane32_swap_b32_e32 v13, v29
	v_permlane32_swap_b32_e32 v14, v30
	v_permlane32_swap_b32_e32 v15, v31
	v_permlane32_swap_b32_e32 v16, v32
	v_permlane32_swap_b32_e32 v17, v33
	v_permlane32_swap_b32_e32 v34, v50
	v_permlane32_swap_b32_e32 v35, v51
	v_permlane32_swap_b32_e32 v36, v52
	v_permlane32_swap_b32_e32 v37, v53
	v_permlane32_swap_b32_e32 v38, v54
	v_permlane32_swap_b32_e32 v39, v55
	v_permlane32_swap_b32_e32 v40, v56
	v_permlane32_swap_b32_e32 v41, v57
	v_permlane32_swap_b32_e32 v42, v58
	v_permlane32_swap_b32_e32 v43, v59
	v_permlane32_swap_b32_e32 v44, v60
	v_permlane32_swap_b32_e32 v45, v61
	v_permlane32_swap_b32_e32 v46, v62
	v_permlane32_swap_b32_e32 v47, v63
	v_permlane32_swap_b32_e32 v48, v64
	v_permlane32_swap_b32_e32 v49, v65
	v_fmac_f32_e32 v2, v128, v157
	v_fmac_f32_e32 v34, v127, v156
	v_fmac_f32_e32 v2, v126, v156
	v_fmac_f32_e32 v34, v126, v157
	v_fmac_f32_e32 v3, v128, v34
	v_fmac_f32_e32 v35, v127, v2
	v_fmac_f32_e32 v3, v126, v2
	v_fmac_f32_e32 v35, v126, v34
	v_cvt_pk_bf16_f32 v242, v2, v34
	v_cvt_pk_bf16_f32 v243, v3, v35
	ds_write2_b32 v197, v242, v243 offset0:0 offset1:68
	v_fmac_f32_e32 v4, v128, v35
	v_fmac_f32_e32 v36, v127, v3
	v_fmac_f32_e32 v4, v126, v3
	v_fmac_f32_e32 v36, v126, v35
	v_fmac_f32_e32 v5, v128, v36
	v_fmac_f32_e32 v37, v127, v4
	v_fmac_f32_e32 v5, v126, v4
	v_fmac_f32_e32 v37, v126, v36
	v_cvt_pk_bf16_f32 v244, v4, v36
	v_cvt_pk_bf16_f32 v245, v5, v37
	ds_write2_b32 v197, v244, v245 offset0:136 offset1:204
	v_fmac_f32_e32 v18, v128, v37
	v_fmac_f32_e32 v50, v127, v5
	v_fmac_f32_e32 v18, v126, v5
	v_fmac_f32_e32 v50, v126, v37
	v_fmac_f32_e32 v19, v128, v50
	v_fmac_f32_e32 v51, v127, v18
	v_fmac_f32_e32 v19, v126, v18
	v_fmac_f32_e32 v51, v126, v50
	v_cvt_pk_bf16_f32 v242, v18, v50
	v_cvt_pk_bf16_f32 v243, v19, v51
	ds_write2_b32 v235, v242, v243 offset0:0 offset1:68
	v_fmac_f32_e32 v20, v128, v51
	v_fmac_f32_e32 v52, v127, v19
	v_fmac_f32_e32 v20, v126, v19
	v_fmac_f32_e32 v52, v126, v51
	v_fmac_f32_e32 v21, v128, v52
	v_fmac_f32_e32 v53, v127, v20
	v_fmac_f32_e32 v21, v126, v20
	v_fmac_f32_e32 v53, v126, v52
	v_cvt_pk_bf16_f32 v244, v20, v52
	v_cvt_pk_bf16_f32 v245, v21, v53
	ds_write2_b32 v235, v244, v245 offset0:136 offset1:204
	v_fmac_f32_e32 v6, v128, v53
	v_fmac_f32_e32 v38, v127, v21
	v_fmac_f32_e32 v6, v126, v21
	v_fmac_f32_e32 v38, v126, v53
	v_fmac_f32_e32 v7, v128, v38
	v_fmac_f32_e32 v39, v127, v6
	v_fmac_f32_e32 v7, v126, v6
	v_fmac_f32_e32 v39, v126, v38
	v_cvt_pk_bf16_f32 v242, v6, v38
	v_cvt_pk_bf16_f32 v243, v7, v39
	ds_write2_b32 v236, v242, v243 offset0:0 offset1:68
	v_fmac_f32_e32 v8, v128, v39
	v_fmac_f32_e32 v40, v127, v7
	v_fmac_f32_e32 v8, v126, v7
	v_fmac_f32_e32 v40, v126, v39
	v_fmac_f32_e32 v9, v128, v40
	v_fmac_f32_e32 v41, v127, v8
	v_fmac_f32_e32 v9, v126, v8
	v_fmac_f32_e32 v41, v126, v40
	v_cvt_pk_bf16_f32 v244, v8, v40
	v_cvt_pk_bf16_f32 v245, v9, v41
	ds_write2_b32 v236, v244, v245 offset0:136 offset1:204
	v_fmac_f32_e32 v22, v128, v41
	v_fmac_f32_e32 v54, v127, v9
	v_fmac_f32_e32 v22, v126, v9
	v_fmac_f32_e32 v54, v126, v41
	v_fmac_f32_e32 v23, v128, v54
	v_fmac_f32_e32 v55, v127, v22
	v_fmac_f32_e32 v23, v126, v22
	v_fmac_f32_e32 v55, v126, v54
	v_cvt_pk_bf16_f32 v242, v22, v54
	v_cvt_pk_bf16_f32 v243, v23, v55
; #define LAS __attribute__((address_space(3)))
; __device__ __forceinline__ unsigned pk2(float lo, float hi) { const f32x2 v = {lo, hi}; return __builtin_bit_cast(unsigned, __builtin_convertvector(v, bf16x2_t)); }
; __device__ __forceinline__ float bflo(unsigned w) { return __uint_as_float(w << 16); }
; __device__ __forceinline__ float bfhi(unsigned w) { return __uint_as_float(w & 0xffff0000u); }
; #define LDS_FENCE() asm volatile("s_waitcnt lgkmcnt(0)" ::: "memory")
; template <bool BWD, int MODE  >
; __device__ __forceinline__ void ssm_pass(const bf16* proj, int rowbase, int g, const bf16x8* BBp, const bf16x8* CCp, float ar, float ai, float& sr, float& si,
;                                          LAS unsigned* XS, int lane, f32x4* ysc, const float* Dp, bf16* zbuf) {
;     ...
;         for (int tt = 0; tt < 32; ++tt) {
;             const int t = BWD ? 31 - tt : tt;
;             const unsigned v = XS[t * XS_STRIDE + lane];
;             const float nr = fmaf(ar, sr, fmaf(-ai, si, bflo(v))), ni = fmaf(ar, si, fmaf(ai, sr, bfhi(v)));
;             sr = nr; si = ni;
;             if (MODE > 0) XS[t * XS_STRIDE + lane] = pk2(sr, si);
;         }
;         if (MODE > 0) {
;             LDS_FENCE();
;             const LAS unsigned char* ab = (const LAS unsigned char*)XS + (lane & 15) * (XS_STRIDE * 4) + (lane >> 4) * 16;
; #pragma unroll
;             for (int kk = 0; kk < 4; ++kk) {
;                 const bf16x8 a0 = *(const LAS bf16x8*)(ab + kk * 64), a1 = *(const LAS bf16x8*)(ab + 16 * XS_STRIDE * 4 + kk * 64);
;                 y0 = __builtin_amdgcn_mfma_f32_16x16x32_bf16(a0, cc[kk], y0, 0, 0, 0);
;                 y1 = __builtin_amdgcn_mfma_f32_16x16x32_bf16(a1, cc[kk], y1, 0, 0, 0);
;             }
	ds_write2_b32 v237, v242, v243 offset0:0 offset1:68
	v_fmac_f32_e32 v24, v128, v55
	v_fmac_f32_e32 v56, v127, v23
	v_fmac_f32_e32 v24, v126, v23
	v_fmac_f32_e32 v56, v126, v55
	v_fmac_f32_e32 v25, v128, v56
	v_fmac_f32_e32 v57, v127, v24
	v_fmac_f32_e32 v25, v126, v24
	v_fmac_f32_e32 v57, v126, v56
	v_cvt_pk_bf16_f32 v244, v24, v56
	v_cvt_pk_bf16_f32 v245, v25, v57
	ds_write2_b32 v237, v244, v245 offset0:136 offset1:204
	v_fmac_f32_e32 v10, v128, v57
	v_fmac_f32_e32 v42, v127, v25
	v_fmac_f32_e32 v10, v126, v25
	v_fmac_f32_e32 v42, v126, v57
	v_fmac_f32_e32 v11, v128, v42
	v_fmac_f32_e32 v43, v127, v10
	v_fmac_f32_e32 v11, v126, v10
	v_fmac_f32_e32 v43, v126, v42
	v_cvt_pk_bf16_f32 v242, v10, v42
	v_cvt_pk_bf16_f32 v243, v11, v43
	ds_write2_b32 v238, v242, v243 offset0:0 offset1:68
	v_fmac_f32_e32 v12, v128, v43
	v_fmac_f32_e32 v44, v127, v11
	v_fmac_f32_e32 v12, v126, v11
	v_fmac_f32_e32 v44, v126, v43
	v_fmac_f32_e32 v13, v128, v44
	v_fmac_f32_e32 v45, v127, v12
	v_fmac_f32_e32 v13, v126, v12
	v_fmac_f32_e32 v45, v126, v44
	v_cvt_pk_bf16_f32 v244, v12, v44
	v_cvt_pk_bf16_f32 v245, v13, v45
	ds_write2_b32 v238, v244, v245 offset0:136 offset1:204
	v_fmac_f32_e32 v26, v128, v45
	v_fmac_f32_e32 v58, v127, v13
	v_fmac_f32_e32 v26, v126, v13
	v_fmac_f32_e32 v58, v126, v45
	v_fmac_f32_e32 v27, v128, v58
	v_fmac_f32_e32 v59, v127, v26
	v_fmac_f32_e32 v27, v126, v26
	v_fmac_f32_e32 v59, v126, v58
	v_cvt_pk_bf16_f32 v242, v26, v58
	v_cvt_pk_bf16_f32 v243, v27, v59
	ds_write2_b32 v239, v242, v243 offset0:0 offset1:68
	v_fmac_f32_e32 v28, v128, v59
	v_fmac_f32_e32 v60, v127, v27
	v_fmac_f32_e32 v28, v126, v27
	v_fmac_f32_e32 v60, v126, v59
	v_fmac_f32_e32 v29, v128, v60
	v_fmac_f32_e32 v61, v127, v28
	v_fmac_f32_e32 v29, v126, v28
	v_fmac_f32_e32 v61, v126, v60
	v_cvt_pk_bf16_f32 v244, v28, v60
	v_cvt_pk_bf16_f32 v245, v29, v61
	ds_write2_b32 v239, v244, v245 offset0:136 offset1:204
	v_fmac_f32_e32 v14, v128, v61
	v_fmac_f32_e32 v46, v127, v29
	v_fmac_f32_e32 v14, v126, v29
	v_fmac_f32_e32 v46, v126, v61
	v_fmac_f32_e32 v15, v128, v46
	v_fmac_f32_e32 v47, v127, v14
	v_fmac_f32_e32 v15, v126, v14
	v_fmac_f32_e32 v47, v126, v46
	v_cvt_pk_bf16_f32 v242, v14, v46
	v_cvt_pk_bf16_f32 v243, v15, v47
	ds_write2_b32 v240, v242, v243 offset0:0 offset1:68
	v_fmac_f32_e32 v16, v128, v47
	v_fmac_f32_e32 v48, v127, v15
	v_fmac_f32_e32 v16, v126, v15
	v_fmac_f32_e32 v48, v126, v47
	v_fmac_f32_e32 v17, v128, v48
	v_fmac_f32_e32 v49, v127, v16
	v_fmac_f32_e32 v17, v126, v16
	v_fmac_f32_e32 v49, v126, v48
	v_cvt_pk_bf16_f32 v244, v16, v48
	v_cvt_pk_bf16_f32 v245, v17, v49
	ds_write2_b32 v240, v244, v245 offset0:136 offset1:204
	v_fmac_f32_e32 v30, v128, v49
	v_fmac_f32_e32 v62, v127, v17
	v_fmac_f32_e32 v30, v126, v17
	v_fmac_f32_e32 v62, v126, v49
	v_fmac_f32_e32 v31, v128, v62
	v_fmac_f32_e32 v63, v127, v30
	v_fmac_f32_e32 v31, v126, v30
	v_fmac_f32_e32 v63, v126, v62
	v_cvt_pk_bf16_f32 v242, v30, v62
	v_cvt_pk_bf16_f32 v243, v31, v63
	ds_write2_b32 v241, v242, v243 offset0:0 offset1:68
	v_fmac_f32_e32 v32, v128, v63
	v_fmac_f32_e32 v64, v127, v31
	v_fmac_f32_e32 v32, v126, v31
	v_fmac_f32_e32 v64, v126, v63
	v_fmac_f32_e32 v33, v128, v64
	v_fmac_f32_e32 v65, v127, v32
	v_fmac_f32_e32 v33, v126, v32
	v_fmac_f32_e32 v65, v126, v64
	v_cvt_pk_bf16_f32 v244, v32, v64
	v_cvt_pk_bf16_f32 v245, v33, v65
	ds_write2_b32 v241, v244, v245 offset0:136 offset1:204
	v_mov_b32_e32 v156, v33
	v_mov_b32_e32 v157, v65
	s_waitcnt vmcnt(0)
	v_mov_b32_e32 v7, v226
	v_mov_b32_e32 v28, v227
	v_mov_b32_e32 v29, v228
	v_mov_b32_e32 v6, v229
	v_mov_b32_e32 v5, v230
	v_mov_b32_e32 v4, v231
	v_mov_b32_e32 v3, v232
	v_mov_b32_e32 v2, v233
	s_waitcnt lgkmcnt(0)
	ds_read_b128 v[8:11], v178 offset:16384
	ds_read_b128 v[12:15], v178 offset:16448
	s_waitcnt vmcnt(9) lgkmcnt(1)
	v_mfma_f32_16x16x32_bf16 v[8:11], v[8:11], v[90:93], v[106:109]
	ds_read_b128 v[16:19], v178 offset:20736
	ds_read_b128 v[20:23], v178 offset:20800
	ds_read_b128 v[24:27], v178 offset:16576
	s_waitcnt vmcnt(7)
	v_lshlrev_b32_e32 v7, 16, v7
	s_waitcnt lgkmcnt(3)
	v_mfma_f32_16x16x32_bf16 v[8:11], v[12:15], v[74:77], v[8:11]
	ds_read_b128 v[12:15], v178 offset:16512
	s_waitcnt vmcnt(4)
	v_lshlrev_b32_e32 v6, 16, v6
	s_waitcnt vmcnt(3)
	v_lshlrev_b32_e32 v5, 16, v5
	s_waitcnt lgkmcnt(3)
	v_mfma_f32_16x16x32_bf16 v[16:19], v[16:19], v[90:93], v[102:105]
	s_waitcnt vmcnt(2)
; __device__ __forceinline__ unsigned f2bf(float f) { unsigned u = __builtin_bit_cast(unsigned, f); return (u + 0x7fffu + ((u >> 16) & 1u)) >> 16; }
; __device__ __forceinline__ float bf2f(bf16 v) { return __uint_as_float((unsigned)v << 16); }
; #define LDS_FENCE() asm volatile("s_waitcnt lgkmcnt(0)" ::: "memory")
; template <bool BWD, int MODE  >
; __device__ __forceinline__ void ssm_pass(const bf16* proj, int rowbase, int g, const bf16x8* BBp, const bf16x8* CCp, float ar, float ai, float& sr, float& si,
;                                          LAS unsigned* XS, int lane, f32x4* ysc, const float* Dp, bf16* zbuf) {
;     ...
;                 const int hcol = g * 16 + (lane & 15);
; #pragma unroll
;                 for (int rt = 0; rt < 2; ++rt)
; #pragma unroll
;                     for (int i = 0; i < 4; ++i) {
;                         const int row = rowbase + 32 * ch + 16 * rt + 4 * (lane >> 4) + i;
;                         const float uv = bf2f(uvl[rt * 4 + i]);
;                         const float y = (rt ? y1[i] : y0[i]) + dval * uv;
;                         const float zz = y * __builtin_amdgcn_rcpf(1.0f + __builtin_amdgcn_exp2f(-2.3022082f * (y + 0.044715f * y * y * y)));
;                         zbuf[(size_t)row * 512 + hcol] = (bf16)f2bf(zz);
;                     }
;             }
;             LDS_FENCE();
;         }
;         ucur = unext;
	v_lshlrev_b32_e32 v4, 16, v4
	s_waitcnt vmcnt(1)
	v_lshlrev_b32_e32 v3, 16, v3
	s_waitcnt vmcnt(0)
	v_lshlrev_b32_e32 v2, 16, v2
	s_waitcnt lgkmcnt(0)
	v_mfma_f32_16x16x32_bf16 v[8:11], v[12:15], v[78:81], v[8:11]
	ds_read_b128 v[12:15], v178 offset:20928
	s_mov_b64 s[28:29], 0x14000
	v_lshl_add_u64 v[136:137], v[136:137], 0, s[28:29]
	v_mfma_f32_16x16x32_bf16 v[16:19], v[20:23], v[74:77], v[16:19]
	ds_read_b128 v[20:23], v178 offset:20864
	s_add_i32 s26, s26, 32
	s_mov_b64 s[28:29], 0x800
	v_mfma_f32_16x16x32_bf16 v[8:11], v[24:27], v[94:97], v[8:11]
	v_mov_b64_e32 v[50:51], v[98:99]
	v_lshl_add_u64 v[138:139], v[138:139], 0, s[28:29]
	s_cmpk_lg_i32 s26, 0x200
	s_waitcnt lgkmcnt(0)
	v_mfma_f32_16x16x32_bf16 v[16:19], v[20:23], v[78:81], v[16:19]
	v_mov_b64_e32 v[52:53], v[100:101]
	s_nop 1
	v_fma_f32 v7, v0, v7, v8
	v_mul_f32_e32 v8, 0x3d372713, v7
	v_mul_f32_e32 v8, v7, v8
	v_fma_f32 v8, v7, v8, v7
	v_mul_f32_e32 v8, 0xc0135761, v8
	v_exp_f32_e32 v8, v8
	v_mfma_f32_16x16x32_bf16 v[12:15], v[12:15], v[94:97], v[16:19]
	v_fmac_f32_e32 v11, v0, v6
	v_mul_f32_e32 v6, 0x3d372713, v11
	v_add_f32_e32 v8, 1.0, v8
	v_lshlrev_b32_e32 v16, 16, v28
	v_fma_f32 v16, v0, v16, v9
	v_mul_f32_e32 v9, 0x3d372713, v16
	v_mul_f32_e32 v9, v16, v9
	v_rcp_f32_e32 v8, v8
	v_fma_f32 v9, v16, v9, v16
	v_mul_f32_e32 v9, 0xc0135761, v9
	v_exp_f32_e32 v9, v9
	v_mul_f32_e32 v7, v7, v8
	v_bfe_u32 v8, v7, 16, 1
	v_add3_u32 v7, v7, v8, s72
	v_add_f32_e32 v8, 1.0, v9
	v_rcp_f32_e32 v17, v8
	v_lshlrev_b64 v[8:9], 10, v[150:151]
	v_lshl_add_u64 v[8:9], v[130:131], 0, v[8:9]
	global_store_short_d16_hi v[8:9], v7, off
	v_mul_f32_e32 v7, v16, v17
	v_bfe_u32 v8, v7, 16, 1
	v_add3_u32 v7, v7, v8, s72
	v_lshlrev_b32_e32 v8, 16, v29
	v_fma_f32 v10, v0, v8, v10
	v_mul_f32_e32 v8, 0x3d372713, v10
	v_mul_f32_e32 v8, v10, v8
	v_fma_f32 v8, v10, v8, v10
	v_mul_f32_e32 v8, 0xc0135761, v8
	v_exp_f32_e32 v16, v8
	v_mul_f32_e32 v6, v11, v6
	v_lshlrev_b64 v[8:9], 10, v[154:155]
	v_fma_f32 v6, v11, v6, v11
	v_lshl_add_u64 v[8:9], v[130:131], 0, v[8:9]
	v_mul_f32_e32 v6, 0xc0135761, v6
	global_store_short_d16_hi v[8:9], v7, off
	v_add_f32_e32 v7, 1.0, v16
	v_exp_f32_e32 v6, v6
	v_rcp_f32_e32 v7, v7
	v_fma_f32 v5, v0, v5, v12
	v_fma_f32 v3, v0, v3, v14
	v_add_f32_e32 v6, 1.0, v6
	v_mul_f32_e32 v7, v10, v7
	v_rcp_f32_e32 v9, v6
	v_bfe_u32 v8, v7, 16, 1
	v_add3_u32 v8, v7, v8, s72
	v_lshlrev_b64 v[6:7], 10, v[152:153]
	v_lshl_add_u64 v[6:7], v[130:131], 0, v[6:7]
	global_store_short_d16_hi v[6:7], v8, off
	v_mul_f32_e32 v6, v11, v9
	v_bfe_u32 v7, v6, 16, 1
	v_add3_u32 v8, v6, v7, s72
	v_mul_f32_e32 v6, 0x3d372713, v5
	v_mul_f32_e32 v6, v5, v6
	v_fma_f32 v6, v5, v6, v5
	v_mul_f32_e32 v6, 0xc0135761, v6
	v_exp_f32_e32 v9, v6
	v_lshlrev_b64 v[6:7], 10, v[148:149]
	v_lshl_add_u64 v[6:7], v[130:131], 0, v[6:7]
	global_store_short_d16_hi v[6:7], v8, off
	v_fma_f32 v7, v0, v4, v13
	v_mul_f32_e32 v4, 0x3d372713, v7
	v_mul_f32_e32 v4, v7, v4
	v_fma_f32 v4, v7, v4, v7
	v_mul_f32_e32 v4, 0xc0135761, v4
	v_add_f32_e32 v6, 1.0, v9
	v_exp_f32_e32 v4, v4
	v_rcp_f32_e32 v6, v6
	v_fmac_f32_e32 v15, v0, v2
	v_mul_f32_e32 v2, 0x3d372713, v15
	v_add_f32_e32 v4, 1.0, v4
	v_mul_f32_e32 v5, v5, v6
	v_rcp_f32_e32 v8, v4
	v_bfe_u32 v6, v5, 16, 1
	v_add3_u32 v6, v5, v6, s72
	v_lshlrev_b64 v[4:5], 10, v[146:147]
	v_lshl_add_u64 v[4:5], v[130:131], 0, v[4:5]
	global_store_short_d16_hi v[4:5], v6, off
	v_mul_f32_e32 v4, v7, v8
	v_bfe_u32 v5, v4, 16, 1
	v_add3_u32 v6, v4, v5, s72
	v_mul_f32_e32 v4, 0x3d372713, v3
	v_mul_f32_e32 v4, v3, v4
	v_fma_f32 v4, v3, v4, v3
	v_mul_f32_e32 v4, 0xc0135761, v4
	v_exp_f32_e32 v7, v4
	v_mul_f32_e32 v2, v15, v2
	v_lshlrev_b64 v[4:5], 10, v[144:145]
	v_fma_f32 v2, v15, v2, v15
	v_lshl_add_u64 v[4:5], v[130:131], 0, v[4:5]
	v_mul_f32_e32 v2, 0xc0135761, v2
	global_store_short_d16_hi v[4:5], v6, off
	v_add_f32_e32 v4, 1.0, v7
	v_exp_f32_e32 v2, v2
	v_rcp_f32_e32 v4, v4
	v_add_f32_e32 v2, 1.0, v2
	v_mul_f32_e32 v3, v3, v4
	v_rcp_f32_e32 v5, v2
	v_bfe_u32 v4, v3, 16, 1
	v_add3_u32 v4, v3, v4, s72
	v_lshlrev_b64 v[2:3], 10, v[142:143]
	v_lshl_add_u64 v[2:3], v[130:131], 0, v[2:3]
	global_store_short_d16_hi v[2:3], v4, off
	v_mul_f32_e32 v2, v15, v5
	v_bfe_u32 v3, v2, 16, 1
	v_add3_u32 v4, v2, v3, s72
	v_lshlrev_b64 v[2:3], 10, v[140:141]
	v_lshl_add_u64 v[2:3], v[130:131], 0, v[2:3]
	global_store_short_d16_hi v[2:3], v4, off
	s_waitcnt lgkmcnt(0)
	s_cbranch_scc0 .LBB0_504

; #define PG8_STAGE(bufoff, gbase, voff) do { _Pragma("unroll") for (int _i = 0; _i < 2; ++_i) \
;         __builtin_amdgcn_global_load_lds((const unsigned*)((const char*)(gbase) + (voff)[_i]), (PG8_LAS unsigned*)(lds + (bufoff) + ldsw + _i * 8192), 16, 0, 0); } while (0)
; #define PG8_LDA(dst, b, h) do { _Pragma("unroll") for (int m = 0; m < 4; ++m) _Pragma("unroll") for (int k = 0; k < 2; ++k) dst[m][k] = *(const PG8_LAS bf16x8*)(lds + PG8_SA(b, h) + aoff + m * 2048 + k * 1024); } while (0)
; #define PG8_LDB(dst, b, h) do { _Pragma("unroll") for (int n = 0; n < 2; ++n) _Pragma("unroll") for (int k = 0; k < 2; ++k) dst[n][k] = *(const PG8_LAS bf16x8*)(lds + PG8_SB(b, h) + boff + n * 2048 + k * 1024); } while (0)
; #define PG8_MMA(ai, bj, At, Bt) do { __builtin_amdgcn_s_setprio(1); _Pragma("unroll") for (int m = 0; m < 4; ++m) _Pragma("unroll") for (int n = 0; n < 2; ++n) _Pragma("unroll") for (int k = 0; k < 2; ++k) \
;         acc[ai][bj][m][n] = __builtin_amdgcn_mfma_f32_16x16x32_bf16(Bt[n][k], At[m][k], acc[ai][bj][m][n], 0, 0, 0); __builtin_amdgcn_s_setprio(0); } while (0)
; #define PG8_WAIT_V(n) asm volatile("s_waitcnt vmcnt(" #n ")" ::: "memory")
; #define PG8_WAIT_L(n) asm volatile("s_waitcnt lgkmcnt(" #n ")" ::: "memory")
; #define PG8_BAR __builtin_amdgcn_s_barrier()
; #define PG8_SCHED __builtin_amdgcn_sched_barrier(0)
; template <class Epi, class Sched, bool ALIGN_EPI = false, bool SP2 = false>
; __device__ __forceinline__ void gemm_phase(PG8_LAS unsigned char* lds, const Gemm g, const Sched& S, const Epi& E) {
;     ...
;             PG8_LDB(B0, 0, 0); PG8_LDB(B1, 0, 1); PG8_SCHED; PG8_LDA(At, 0, 0); PG8_STAGE(PG8_SA(1, 1), a1 + hstep, voffA);
;             PG8_WAIT_V(8); PG8_WAIT_L(0); PG8_BAR; PG8_MMA(0, 0, At, B0); PG8_MMA(0, 1, At, B1); PG8_BAR; PG8_SCHED;
;             PG8_LDA(At, 0, 1); PG8_STAGE(PG8_SB(0, 0), b2, voffB); PG8_STAGE(PG8_SB(0, 1), b2 + hstep, voffB); PG8_STAGE(PG8_SA(0, 0), a2, voffA);
;             PG8_WAIT_V(8); PG8_WAIT_L(0); PG8_BAR; PG8_MMA(1, 0, At, B0); PG8_MMA(1, 1, At, B1); PG8_BAR; PG8_SCHED;
.LBB0_587:
	s_add_u32 s27, s94, 0xfffe0080
	s_addc_u32 s28, s95, -1
	s_add_i32 s29, 0, 0x10000
	s_cmp_eq_u32 s26, 4
	s_cselect_b32 vcc_hi, s22, s28
	s_cselect_b32 vcc_lo, s23, s27
	v_add_u32_e32 v144, s29, v147
	s_cselect_b32 s97, s52, s93
	s_cselect_b32 s96, s85, s87
	s_add_i32 s27, 0, 0x14000
	ds_read_b128 v[140:143], v144
	ds_read_b128 v[150:153], v144 offset:1024
	ds_read_b128 v[154:157], v144 offset:2048
	ds_read_b128 v[158:161], v144 offset:3072
	v_add_u32_e32 v144, s27, v147
	ds_read_b128 v[178:181], v144
	ds_read_b128 v[182:185], v144 offset:1024
	ds_read_b128 v[186:189], v144 offset:2048
	ds_read_b128 v[190:193], v144 offset:3072
	s_add_i32 m0, s61, 0xc000
	ds_read_b128 v[194:197], v149
	ds_read_b128 v[198:201], v149 offset:1024
	ds_read_b128 v[202:205], v149 offset:2048
	ds_read_b128 v[210:213], v149 offset:3072
	ds_read_b128 v[214:217], v149 offset:4096
	ds_read_b128 v[226:229], v149 offset:5120
	ds_read_b128 v[230:233], v149 offset:6144
	ds_read_b128 v[234:237], v149 offset:7168
	global_load_lds_dwordx4 v136, s[94:95]
	s_add_i32 m0, s61, 0xe000
	s_nop 0
	global_load_lds_dwordx4 v138, s[94:95]
	s_waitcnt vmcnt(8)
	s_waitcnt lgkmcnt(0)
	s_barrier
	s_setprio 1
	s_waitcnt lgkmcnt(0)
	v_mfma_f32_16x16x32_bf16 v[126:129], v[140:143], v[194:197], v[126:129]
	v_mfma_f32_16x16x32_bf16 v[122:125], v[154:157], v[194:197], v[122:125]
	v_mfma_f32_16x16x32_bf16 v[110:113], v[140:143], v[202:205], v[110:113]
	v_mfma_f32_16x16x32_bf16 v[106:109], v[154:157], v[202:205], v[106:109]
	v_mfma_f32_16x16x32_bf16 v[94:97], v[140:143], v[214:217], v[94:97]
	v_mfma_f32_16x16x32_bf16 v[90:93], v[154:157], v[214:217], v[90:93]
	v_mfma_f32_16x16x32_bf16 v[78:81], v[140:143], v[230:233], v[78:81]
	v_mfma_f32_16x16x32_bf16 v[74:77], v[154:157], v[230:233], v[74:77]
	v_mfma_f32_16x16x32_bf16 v[126:129], v[150:153], v[198:201], v[126:129]
	v_mfma_f32_16x16x32_bf16 v[122:125], v[158:161], v[198:201], v[122:125]
	v_mfma_f32_16x16x32_bf16 v[110:113], v[150:153], v[210:213], v[110:113]
	v_mfma_f32_16x16x32_bf16 v[106:109], v[158:161], v[210:213], v[106:109]
	v_mfma_f32_16x16x32_bf16 v[94:97], v[150:153], v[226:229], v[94:97]
	v_mfma_f32_16x16x32_bf16 v[90:93], v[158:161], v[226:229], v[90:93]
	v_mfma_f32_16x16x32_bf16 v[78:81], v[150:153], v[234:237], v[78:81]
	v_mfma_f32_16x16x32_bf16 v[74:77], v[158:161], v[234:237], v[74:77]
	s_setprio 0
	s_setprio 1
	v_mfma_f32_16x16x32_bf16 v[118:121], v[178:181], v[194:197], v[118:121]
	v_mfma_f32_16x16x32_bf16 v[114:117], v[186:189], v[194:197], v[114:117]
	v_mfma_f32_16x16x32_bf16 v[102:105], v[178:181], v[202:205], v[102:105]
	v_mfma_f32_16x16x32_bf16 v[98:101], v[186:189], v[202:205], v[98:101]
	v_mfma_f32_16x16x32_bf16 v[86:89], v[178:181], v[214:217], v[86:89]
	v_mfma_f32_16x16x32_bf16 v[82:85], v[186:189], v[214:217], v[82:85]
	v_mfma_f32_16x16x32_bf16 v[70:73], v[178:181], v[230:233], v[70:73]
	v_mfma_f32_16x16x32_bf16 v[66:69], v[186:189], v[230:233], v[66:69]
	v_mfma_f32_16x16x32_bf16 v[118:121], v[182:185], v[198:201], v[118:121]
	v_mfma_f32_16x16x32_bf16 v[114:117], v[190:193], v[198:201], v[114:117]
	v_mfma_f32_16x16x32_bf16 v[102:105], v[182:185], v[210:213], v[102:105]
	v_mfma_f32_16x16x32_bf16 v[98:101], v[190:193], v[210:213], v[98:101]
	v_mfma_f32_16x16x32_bf16 v[86:89], v[182:185], v[226:229], v[86:89]
	v_mfma_f32_16x16x32_bf16 v[82:85], v[190:193], v[226:229], v[82:85]
	v_mfma_f32_16x16x32_bf16 v[70:73], v[182:185], v[234:237], v[70:73]
	v_mfma_f32_16x16x32_bf16 v[66:69], v[190:193], v[234:237], v[66:69]
	s_setprio 0
	s_barrier
	s_add_i32 s28, s29, s60
	s_mov_b32 m0, s28
	ds_read_b128 v[194:197], v149 offset:16384
	ds_read_b128 v[198:201], v149 offset:17408
	ds_read_b128 v[202:205], v149 offset:18432
	ds_read_b128 v[210:213], v149 offset:19456
	ds_read_b128 v[214:217], v149 offset:20480
	ds_read_b128 v[226:229], v149 offset:21504
	ds_read_b128 v[230:233], v149 offset:22528
	ds_read_b128 v[234:237], v149 offset:23552
	global_load_lds_dwordx4 v0, s[96:97]
	s_add_i32 m0, s28, 0x2000
	s_add_u32 s28, s96, 0x20000
	s_addc_u32 s29, s97, 0
	s_add_i32 s27, s27, s60
	global_load_lds_dwordx4 v130, s[96:97]
	s_mov_b32 m0, s27
	s_nop 0
	global_load_lds_dwordx4 v0, s[28:29]
	s_add_i32 m0, s27, 0x2000
	s_nop 0
	global_load_lds_dwordx4 v130, s[28:29]
	s_mov_b32 m0, s61
	s_nop 0
	global_load_lds_dwordx4 v134, vcc
	s_mov_b32 m0, s62
	s_nop 0
	global_load_lds_dwordx4 v132, vcc
	s_waitcnt vmcnt(8)
	s_waitcnt lgkmcnt(0)
	s_barrier
	s_setprio 1
	s_waitcnt lgkmcnt(0)
	v_mfma_f32_16x16x32_bf16 v[62:65], v[140:143], v[194:197], v[62:65]
	v_mfma_f32_16x16x32_bf16 v[58:61], v[154:157], v[194:197], v[58:61]
	v_mfma_f32_16x16x32_bf16 v[46:49], v[140:143], v[202:205], v[46:49]
	v_mfma_f32_16x16x32_bf16 v[42:45], v[154:157], v[202:205], v[42:45]
	v_mfma_f32_16x16x32_bf16 v[30:33], v[140:143], v[214:217], v[30:33]
	v_mfma_f32_16x16x32_bf16 v[26:29], v[154:157], v[214:217], v[26:29]
	v_mfma_f32_16x16x32_bf16 v[14:17], v[140:143], v[230:233], v[14:17]
	v_mfma_f32_16x16x32_bf16 v[10:13], v[154:157], v[230:233], v[10:13]
	v_mfma_f32_16x16x32_bf16 v[62:65], v[150:153], v[198:201], v[62:65]
	v_mfma_f32_16x16x32_bf16 v[58:61], v[158:161], v[198:201], v[58:61]
	v_mfma_f32_16x16x32_bf16 v[46:49], v[150:153], v[210:213], v[46:49]
	v_mfma_f32_16x16x32_bf16 v[42:45], v[158:161], v[210:213], v[42:45]
	v_mfma_f32_16x16x32_bf16 v[30:33], v[150:153], v[226:229], v[30:33]
	v_mfma_f32_16x16x32_bf16 v[26:29], v[158:161], v[226:229], v[26:29]
	v_mfma_f32_16x16x32_bf16 v[14:17], v[150:153], v[234:237], v[14:17]
	v_mfma_f32_16x16x32_bf16 v[10:13], v[158:161], v[234:237], v[10:13]
	s_setprio 0
	s_setprio 1
	v_mfma_f32_16x16x32_bf16 v[54:57], v[178:181], v[194:197], v[54:57]
	v_mfma_f32_16x16x32_bf16 v[50:53], v[186:189], v[194:197], v[50:53]
	v_mfma_f32_16x16x32_bf16 v[38:41], v[178:181], v[202:205], v[38:41]
	v_mfma_f32_16x16x32_bf16 v[34:37], v[186:189], v[202:205], v[34:37]
	v_mfma_f32_16x16x32_bf16 v[22:25], v[178:181], v[214:217], v[22:25]
	v_mfma_f32_16x16x32_bf16 v[18:21], v[186:189], v[214:217], v[18:21]
	v_mfma_f32_16x16x32_bf16 v[6:9], v[178:181], v[230:233], v[6:9]
	v_mfma_f32_16x16x32_bf16 v[2:5], v[186:189], v[230:233], v[2:5]
	v_mfma_f32_16x16x32_bf16 v[54:57], v[182:185], v[198:201], v[54:57]
	v_mfma_f32_16x16x32_bf16 v[50:53], v[190:193], v[198:201], v[50:53]
	v_mfma_f32_16x16x32_bf16 v[38:41], v[182:185], v[210:213], v[38:41]
	v_mfma_f32_16x16x32_bf16 v[34:37], v[190:193], v[210:213], v[34:37]
	v_mfma_f32_16x16x32_bf16 v[22:25], v[182:185], v[226:229], v[22:25]
	v_mfma_f32_16x16x32_bf16 v[18:21], v[190:193], v[226:229], v[18:21]
	v_mfma_f32_16x16x32_bf16 v[6:9], v[182:185], v[234:237], v[6:9]
	v_mfma_f32_16x16x32_bf16 v[2:5], v[190:193], v[234:237], v[2:5]
	s_setprio 0
	s_barrier
; #define PG8_STAGE(bufoff, gbase, voff) do { _Pragma("unroll") for (int _i = 0; _i < 2; ++_i) \
;         __builtin_amdgcn_global_load_lds((const unsigned*)((const char*)(gbase) + (voff)[_i]), (PG8_LAS unsigned*)(lds + (bufoff) + ldsw + _i * 8192), 16, 0, 0); } while (0)
; #define PG8_LDA(dst, b, h) do { _Pragma("unroll") for (int m = 0; m < 4; ++m) _Pragma("unroll") for (int k = 0; k < 2; ++k) dst[m][k] = *(const PG8_LAS bf16x8*)(lds + PG8_SA(b, h) + aoff + m * 2048 + k * 1024); } while (0)
; #define PG8_LDB(dst, b, h) do { _Pragma("unroll") for (int n = 0; n < 2; ++n) _Pragma("unroll") for (int k = 0; k < 2; ++k) dst[n][k] = *(const PG8_LAS bf16x8*)(lds + PG8_SB(b, h) + boff + n * 2048 + k * 1024); } while (0)
; #define PG8_MMA(ai, bj, At, Bt) do { __builtin_amdgcn_s_setprio(1); _Pragma("unroll") for (int m = 0; m < 4; ++m) _Pragma("unroll") for (int n = 0; n < 2; ++n) _Pragma("unroll") for (int k = 0; k < 2; ++k) \
;         acc[ai][bj][m][n] = __builtin_amdgcn_mfma_f32_16x16x32_bf16(Bt[n][k], At[m][k], acc[ai][bj][m][n], 0, 0, 0); __builtin_amdgcn_s_setprio(0); } while (0)
; #define PG8_WAIT_V(n) asm volatile("s_waitcnt vmcnt(" #n ")" ::: "memory")
; #define PG8_WAIT_L(n) asm volatile("s_waitcnt lgkmcnt(" #n ")" ::: "memory")
; #define PG8_BAR __builtin_amdgcn_s_barrier()
; #define PG8_SCHED __builtin_amdgcn_sched_barrier(0)
; template <class Epi, class Sched, bool ALIGN_EPI = false, bool SP2 = false>
; __device__ __forceinline__ void gemm_phase(PG8_LAS unsigned char* lds, const Gemm g, const Sched& S, const Epi& E) {
;     ...
;             PG8_LDB(B0, 1, 0); PG8_LDB(B1, 1, 1); PG8_SCHED; PG8_LDA(At, 1, 0); PG8_STAGE(PG8_SA(0, 1), a2 + hstep, voffA);
;             PG8_WAIT_V(8); PG8_WAIT_L(0); PG8_BAR; PG8_MMA(0, 0, At, B0); PG8_MMA(0, 1, At, B1); PG8_BAR; PG8_SCHED;
;             PG8_LDA(At, 1, 1); PG8_STAGE(PG8_SB(1, 0), b3, voffB); PG8_STAGE(PG8_SB(1, 1), b3 + hstep, voffB); PG8_STAGE(PG8_SA(1, 0), a3, voffA);
;             PG8_WAIT_V(8); PG8_WAIT_L(0); PG8_BAR; PG8_MMA(1, 0, At, B0); PG8_MMA(1, 1, At, B1); PG8_BAR; PG8_SCHED;
	s_add_i32 s27, 0, 0x18000
	s_add_i32 s45, 0, 0x1c000
	v_add_u32_e32 v158, s27, v147
	v_add_u32_e32 v190, s45, v147
	ds_read_b128 v[140:143], v158
	ds_read_b128 v[150:153], v158 offset:1024
	ds_read_b128 v[154:157], v158 offset:2048
	ds_read_b128 v[158:161], v158 offset:3072
	ds_read_b128 v[178:181], v190
	ds_read_b128 v[182:185], v190 offset:1024
	ds_read_b128 v[186:189], v190 offset:2048
	ds_read_b128 v[190:193], v190 offset:3072
	s_add_u32 s28, vcc_lo, 0x20000
	s_addc_u32 s29, vcc_hi, 0
	s_mov_b32 m0, s63
	ds_read_b128 v[194:197], v149 offset:32768
	ds_read_b128 v[198:201], v149 offset:33792
	ds_read_b128 v[202:205], v149 offset:34816
	ds_read_b128 v[210:213], v149 offset:35840
	ds_read_b128 v[214:217], v149 offset:36864
	ds_read_b128 v[226:229], v149 offset:37888
	ds_read_b128 v[230:233], v149 offset:38912
	ds_read_b128 v[234:237], v149 offset:39936
	global_load_lds_dwordx4 v134, s[28:29]
	s_mov_b32 m0, s64
	s_nop 0
	global_load_lds_dwordx4 v132, s[28:29]
	s_waitcnt vmcnt(8)
	s_waitcnt lgkmcnt(0)
	s_barrier
	s_setprio 1
	s_waitcnt lgkmcnt(0)
	v_mfma_f32_16x16x32_bf16 v[126:129], v[140:143], v[194:197], v[126:129]
	v_mfma_f32_16x16x32_bf16 v[122:125], v[154:157], v[194:197], v[122:125]
	v_mfma_f32_16x16x32_bf16 v[110:113], v[140:143], v[202:205], v[110:113]
	v_mfma_f32_16x16x32_bf16 v[106:109], v[154:157], v[202:205], v[106:109]
	v_mfma_f32_16x16x32_bf16 v[94:97], v[140:143], v[214:217], v[94:97]
	v_mfma_f32_16x16x32_bf16 v[90:93], v[154:157], v[214:217], v[90:93]
	v_mfma_f32_16x16x32_bf16 v[78:81], v[140:143], v[230:233], v[78:81]
	v_mfma_f32_16x16x32_bf16 v[74:77], v[154:157], v[230:233], v[74:77]
	v_mfma_f32_16x16x32_bf16 v[126:129], v[150:153], v[198:201], v[126:129]
	v_mfma_f32_16x16x32_bf16 v[122:125], v[158:161], v[198:201], v[122:125]
	v_mfma_f32_16x16x32_bf16 v[110:113], v[150:153], v[210:213], v[110:113]
	v_mfma_f32_16x16x32_bf16 v[106:109], v[158:161], v[210:213], v[106:109]
	v_mfma_f32_16x16x32_bf16 v[94:97], v[150:153], v[226:229], v[94:97]
	v_mfma_f32_16x16x32_bf16 v[90:93], v[158:161], v[226:229], v[90:93]
	v_mfma_f32_16x16x32_bf16 v[78:81], v[150:153], v[234:237], v[78:81]
	v_mfma_f32_16x16x32_bf16 v[74:77], v[158:161], v[234:237], v[74:77]
	s_setprio 0
	s_setprio 1
	v_mfma_f32_16x16x32_bf16 v[118:121], v[178:181], v[194:197], v[118:121]
	v_mfma_f32_16x16x32_bf16 v[114:117], v[186:189], v[194:197], v[114:117]
	v_mfma_f32_16x16x32_bf16 v[102:105], v[178:181], v[202:205], v[102:105]
	v_mfma_f32_16x16x32_bf16 v[98:101], v[186:189], v[202:205], v[98:101]
	v_mfma_f32_16x16x32_bf16 v[86:89], v[178:181], v[214:217], v[86:89]
	v_mfma_f32_16x16x32_bf16 v[82:85], v[186:189], v[214:217], v[82:85]
	v_mfma_f32_16x16x32_bf16 v[70:73], v[178:181], v[230:233], v[70:73]
	v_mfma_f32_16x16x32_bf16 v[66:69], v[186:189], v[230:233], v[66:69]
	v_mfma_f32_16x16x32_bf16 v[118:121], v[182:185], v[198:201], v[118:121]
	v_mfma_f32_16x16x32_bf16 v[114:117], v[190:193], v[198:201], v[114:117]
	v_mfma_f32_16x16x32_bf16 v[102:105], v[182:185], v[210:213], v[102:105]
	v_mfma_f32_16x16x32_bf16 v[98:101], v[190:193], v[210:213], v[98:101]
	v_mfma_f32_16x16x32_bf16 v[86:89], v[182:185], v[226:229], v[86:89]
	v_mfma_f32_16x16x32_bf16 v[82:85], v[190:193], v[226:229], v[82:85]
	v_mfma_f32_16x16x32_bf16 v[70:73], v[182:185], v[234:237], v[70:73]
	v_mfma_f32_16x16x32_bf16 v[66:69], v[190:193], v[234:237], v[66:69]
	s_setprio 0
	s_barrier
	s_add_i32 s27, s27, s60
	s_mov_b32 m0, s27
	ds_read_b128 v[194:197], v149 offset:49152
	ds_read_b128 v[198:201], v149 offset:50176
	ds_read_b128 v[202:205], v149 offset:51200
	ds_read_b128 v[210:213], v149 offset:52224
	ds_read_b128 v[214:217], v149 offset:53248
	ds_read_b128 v[226:229], v149 offset:54272
	ds_read_b128 v[230:233], v149 offset:55296
	ds_read_b128 v[234:237], v149 offset:56320
	s_add_u32 s100, s96, 0x80
	s_addc_u32 s101, s97, 0
	global_load_lds_dwordx4 v0, s[100:101]
	s_add_i32 m0, s27, 0x2000
	s_add_u32 s28, s96, 0x20080
	s_addc_u32 s29, s97, 0
	s_add_i32 s27, s45, s60
	s_add_u32 s100, s96, 0x80
	s_addc_u32 s101, s97, 0
	global_load_lds_dwordx4 v130, s[100:101]
	s_mov_b32 m0, s27
	s_nop 0
	global_load_lds_dwordx4 v0, s[28:29]
	s_add_i32 m0, s27, 0x2000
	s_nop 0
	global_load_lds_dwordx4 v130, s[28:29]
	s_mov_b32 m0, s39
	s_nop 0
	s_add_u32 s100, vcc_lo, 0x80
	s_addc_u32 s101, vcc_hi, 0
	global_load_lds_dwordx4 v134, s[100:101]
	s_mov_b32 m0, s65
	s_nop 0
	s_add_u32 s100, vcc_lo, 0x80
	s_addc_u32 s101, vcc_hi, 0
	global_load_lds_dwordx4 v132, s[100:101]
	s_waitcnt vmcnt(8)
	s_waitcnt lgkmcnt(0)
	s_barrier
	s_setprio 1
	s_waitcnt lgkmcnt(0)
	v_mfma_f32_16x16x32_bf16 v[62:65], v[140:143], v[194:197], v[62:65]
	v_mfma_f32_16x16x32_bf16 v[58:61], v[154:157], v[194:197], v[58:61]
	v_mfma_f32_16x16x32_bf16 v[46:49], v[140:143], v[202:205], v[46:49]
	v_mfma_f32_16x16x32_bf16 v[42:45], v[154:157], v[202:205], v[42:45]
	v_mfma_f32_16x16x32_bf16 v[30:33], v[140:143], v[214:217], v[30:33]
	v_mfma_f32_16x16x32_bf16 v[26:29], v[154:157], v[214:217], v[26:29]
	v_mfma_f32_16x16x32_bf16 v[14:17], v[140:143], v[230:233], v[14:17]
	v_mfma_f32_16x16x32_bf16 v[10:13], v[154:157], v[230:233], v[10:13]
	v_mfma_f32_16x16x32_bf16 v[62:65], v[150:153], v[198:201], v[62:65]
	v_mfma_f32_16x16x32_bf16 v[58:61], v[158:161], v[198:201], v[58:61]
	v_mfma_f32_16x16x32_bf16 v[46:49], v[150:153], v[210:213], v[46:49]
	v_mfma_f32_16x16x32_bf16 v[42:45], v[158:161], v[210:213], v[42:45]
	v_mfma_f32_16x16x32_bf16 v[30:33], v[150:153], v[226:229], v[30:33]
	v_mfma_f32_16x16x32_bf16 v[26:29], v[158:161], v[226:229], v[26:29]
	v_mfma_f32_16x16x32_bf16 v[14:17], v[150:153], v[234:237], v[14:17]
	v_mfma_f32_16x16x32_bf16 v[10:13], v[158:161], v[234:237], v[10:13]
	s_setprio 0
	s_setprio 1
	v_mfma_f32_16x16x32_bf16 v[54:57], v[178:181], v[194:197], v[54:57]
	v_mfma_f32_16x16x32_bf16 v[50:53], v[186:189], v[194:197], v[50:53]
	v_mfma_f32_16x16x32_bf16 v[38:41], v[178:181], v[202:205], v[38:41]
	v_mfma_f32_16x16x32_bf16 v[34:37], v[186:189], v[202:205], v[34:37]
	v_mfma_f32_16x16x32_bf16 v[22:25], v[178:181], v[214:217], v[22:25]
	v_mfma_f32_16x16x32_bf16 v[18:21], v[186:189], v[214:217], v[18:21]
	v_mfma_f32_16x16x32_bf16 v[6:9], v[178:181], v[230:233], v[6:9]
	v_mfma_f32_16x16x32_bf16 v[2:5], v[186:189], v[230:233], v[2:5]
	v_mfma_f32_16x16x32_bf16 v[54:57], v[182:185], v[198:201], v[54:57]
	v_mfma_f32_16x16x32_bf16 v[50:53], v[190:193], v[198:201], v[50:53]
	v_mfma_f32_16x16x32_bf16 v[38:41], v[182:185], v[210:213], v[38:41]
	v_mfma_f32_16x16x32_bf16 v[34:37], v[190:193], v[210:213], v[34:37]
	v_mfma_f32_16x16x32_bf16 v[22:25], v[182:185], v[226:229], v[22:25]
	v_mfma_f32_16x16x32_bf16 v[18:21], v[190:193], v[226:229], v[18:21]
	v_mfma_f32_16x16x32_bf16 v[6:9], v[182:185], v[234:237], v[6:9]
	v_mfma_f32_16x16x32_bf16 v[2:5], v[190:193], v[234:237], v[2:5]
	s_setprio 0
	s_barrier
	s_add_i32 s26, s26, 2
	s_add_u32 s94, s94, 0x100
	s_addc_u32 s95, s95, 0
	s_add_u32 s87, s87, 0x100
	s_addc_u32 s93, s93, 0
	s_cmp_gt_u32 s26, 5
	s_cbranch_scc0 .LBB0_587
	s_and_b64 vcc, exec, s[82:83]
	s_cbranch_vccz .LBB0_590
	s_barrier

; #define PG8_STAGE(bufoff, gbase, voff) do { _Pragma("unroll") for (int _i = 0; _i < 2; ++_i) \
;         __builtin_amdgcn_global_load_lds((const unsigned*)((const char*)(gbase) + (voff)[_i]), (PG8_LAS unsigned*)(lds + (bufoff) + ldsw + _i * 8192), 16, 0, 0); } while (0)
; #define PG8_LDA(dst, b, h) do { _Pragma("unroll") for (int m = 0; m < 4; ++m) _Pragma("unroll") for (int k = 0; k < 2; ++k) dst[m][k] = *(const PG8_LAS bf16x8*)(lds + PG8_SA(b, h) + aoff + m * 2048 + k * 1024); } while (0)
; #define PG8_LDB(dst, b, h) do { _Pragma("unroll") for (int n = 0; n < 2; ++n) _Pragma("unroll") for (int k = 0; k < 2; ++k) dst[n][k] = *(const PG8_LAS bf16x8*)(lds + PG8_SB(b, h) + boff + n * 2048 + k * 1024); } while (0)
; #define PG8_MMA(ai, bj, At, Bt) do { __builtin_amdgcn_s_setprio(1); _Pragma("unroll") for (int m = 0; m < 4; ++m) _Pragma("unroll") for (int n = 0; n < 2; ++n) _Pragma("unroll") for (int k = 0; k < 2; ++k) \
;         acc[ai][bj][m][n] = __builtin_amdgcn_mfma_f32_16x16x32_bf16(Bt[n][k], At[m][k], acc[ai][bj][m][n], 0, 0, 0); __builtin_amdgcn_s_setprio(0); } while (0)
; #define PG8_WAIT_V(n) asm volatile("s_waitcnt vmcnt(" #n ")" ::: "memory")
; #define PG8_BAR __builtin_amdgcn_s_barrier()
; template <class Epi, class Sched, bool ALIGN_EPI = false, bool SP2 = false>
; __device__ __forceinline__ void gemm_phase(PG8_LAS unsigned char* lds, const Gemm g, const Sched& S, const Epi& E) {
;     ...
;         for (int t = 0; t < nt; t += 2) {
;             const bool last = (t == nt - 2);
;             const char* a1 = cA + (size_t)(t + 1) * kstep;
;             const char* a2 = last ? nA : cA + (size_t)(t + 2) * kstep; const char* b2 = last ? nB : cB + (size_t)(t + 2) * kstep;
;             const char* a3 = a2 + kstep; const char* b3 = b2 + kstep;
;             if (last && has_next) S.a_ready(nxt);
;             if constexpr (SP2) {
;             PG8_LDB(B0, 0, 0); PG8_LDB(B1, 0, 1); PG8_SCHED; PG8_LDA(At, 0, 0); PG8_STAGE(PG8_SA(1, 1), a1 + hstep, voffA);
;             PG8_WAIT_V(8); PG8_WAIT_L(0); PG8_BAR; PG8_MMA(0, 0, At, B0); PG8_MMA(0, 1, At, B1); PG8_BAR; PG8_SCHED;
;             PG8_LDA(At, 0, 1); PG8_STAGE(PG8_SB(0, 0), b2, voffB); PG8_STAGE(PG8_SB(0, 1), b2 + hstep, voffB); PG8_STAGE(PG8_SA(0, 0), a2, voffA);
;             PG8_WAIT_V(8); PG8_WAIT_L(0); PG8_BAR; PG8_MMA(1, 0, At, B0); PG8_MMA(1, 1, At, B1); PG8_BAR; PG8_SCHED;
.LBB0_752:
	s_add_u32 s27, s90, 0xfffc0080
	s_addc_u32 s28, s91, -1
	s_add_i32 s29, 0, 0x10000
	s_cmp_eq_u32 s26, 12
	s_cselect_b32 s95, s22, s28
	s_cselect_b32 s94, s23, s27
	s_cselect_b32 s93, s62, s65
	s_cselect_b32 s92, s63, s64
	s_add_i32 s27, 0, 0x14000
	v_add_u32_e32 v142, s29, v227
	v_add_u32_e32 v158, s27, v227
	ds_read_b128 v[130:133], v142
	ds_read_b128 v[134:137], v142 offset:1024
	ds_read_b128 v[138:141], v142 offset:2048
	ds_read_b128 v[142:145], v142 offset:3072
	ds_read_b128 v[146:149], v158
	ds_read_b128 v[150:153], v158 offset:1024
	ds_read_b128 v[154:157], v158 offset:2048
	ds_read_b128 v[158:161], v158 offset:3072
	s_add_i32 m0, s37, 0xc000
	ds_read_b128 v[192:195], v229
	ds_read_b128 v[196:199], v229 offset:1024
	ds_read_b128 v[200:203], v229 offset:2048
	ds_read_b128 v[204:207], v229 offset:3072
	ds_read_b128 v[210:213], v229 offset:4096
	ds_read_b128 v[214:217], v229 offset:5120
	ds_read_b128 v[230:233], v229 offset:6144
	ds_read_b128 v[234:237], v229 offset:7168
	global_load_lds_dwordx4 v188, s[90:91]
	s_add_i32 m0, s37, 0xe000
	s_nop 0
	global_load_lds_dwordx4 v190, s[90:91]
	s_waitcnt vmcnt(8)
	s_waitcnt lgkmcnt(0)
	s_barrier
	s_setprio 1
	s_waitcnt lgkmcnt(0)
	v_mfma_f32_16x16x32_bf16 v[126:129], v[130:133], v[192:195], v[126:129]
	v_mfma_f32_16x16x32_bf16 v[122:125], v[138:141], v[192:195], v[122:125]
	v_mfma_f32_16x16x32_bf16 v[110:113], v[130:133], v[200:203], v[110:113]
	v_mfma_f32_16x16x32_bf16 v[106:109], v[138:141], v[200:203], v[106:109]
	v_mfma_f32_16x16x32_bf16 v[94:97], v[130:133], v[210:213], v[94:97]
	v_mfma_f32_16x16x32_bf16 v[90:93], v[138:141], v[210:213], v[90:93]
	v_mfma_f32_16x16x32_bf16 v[78:81], v[130:133], v[230:233], v[78:81]
	v_mfma_f32_16x16x32_bf16 v[74:77], v[138:141], v[230:233], v[74:77]
	v_mfma_f32_16x16x32_bf16 v[126:129], v[134:137], v[196:199], v[126:129]
	v_mfma_f32_16x16x32_bf16 v[122:125], v[142:145], v[196:199], v[122:125]
	v_mfma_f32_16x16x32_bf16 v[110:113], v[134:137], v[204:207], v[110:113]
	v_mfma_f32_16x16x32_bf16 v[106:109], v[142:145], v[204:207], v[106:109]
	v_mfma_f32_16x16x32_bf16 v[94:97], v[134:137], v[214:217], v[94:97]
	v_mfma_f32_16x16x32_bf16 v[90:93], v[142:145], v[214:217], v[90:93]
	v_mfma_f32_16x16x32_bf16 v[78:81], v[134:137], v[234:237], v[78:81]
	v_mfma_f32_16x16x32_bf16 v[74:77], v[142:145], v[234:237], v[74:77]
	s_setprio 0
	s_setprio 1
	v_mfma_f32_16x16x32_bf16 v[118:121], v[146:149], v[192:195], v[118:121]
	v_mfma_f32_16x16x32_bf16 v[114:117], v[154:157], v[192:195], v[114:117]
	v_mfma_f32_16x16x32_bf16 v[102:105], v[146:149], v[200:203], v[102:105]
	v_mfma_f32_16x16x32_bf16 v[98:101], v[154:157], v[200:203], v[98:101]
	v_mfma_f32_16x16x32_bf16 v[86:89], v[146:149], v[210:213], v[86:89]
	v_mfma_f32_16x16x32_bf16 v[82:85], v[154:157], v[210:213], v[82:85]
	v_mfma_f32_16x16x32_bf16 v[70:73], v[146:149], v[230:233], v[70:73]
	v_mfma_f32_16x16x32_bf16 v[66:69], v[154:157], v[230:233], v[66:69]
	v_mfma_f32_16x16x32_bf16 v[118:121], v[150:153], v[196:199], v[118:121]
	v_mfma_f32_16x16x32_bf16 v[114:117], v[158:161], v[196:199], v[114:117]
	v_mfma_f32_16x16x32_bf16 v[102:105], v[150:153], v[204:207], v[102:105]
	v_mfma_f32_16x16x32_bf16 v[98:101], v[158:161], v[204:207], v[98:101]
	v_mfma_f32_16x16x32_bf16 v[86:89], v[150:153], v[214:217], v[86:89]
	v_mfma_f32_16x16x32_bf16 v[82:85], v[158:161], v[214:217], v[82:85]
	v_mfma_f32_16x16x32_bf16 v[70:73], v[150:153], v[234:237], v[70:73]
	v_mfma_f32_16x16x32_bf16 v[66:69], v[158:161], v[234:237], v[66:69]
	s_setprio 0
	s_barrier
	s_add_i32 s28, s29, s36
	s_mov_b32 m0, s28
	ds_read_b128 v[192:195], v229 offset:16384
	ds_read_b128 v[196:199], v229 offset:17408
	ds_read_b128 v[200:203], v229 offset:18432
	ds_read_b128 v[204:207], v229 offset:19456
	ds_read_b128 v[210:213], v229 offset:20480
	ds_read_b128 v[214:217], v229 offset:21504
	ds_read_b128 v[230:233], v229 offset:22528
	ds_read_b128 v[234:237], v229 offset:23552
	global_load_lds_dwordx4 v0, s[92:93]
	s_add_i32 m0, s28, 0x2000
	s_add_u32 s28, s92, 0x40000
	s_addc_u32 s29, s93, 0
	s_add_i32 s27, s27, s36
	global_load_lds_dwordx4 v178, s[92:93]
	s_mov_b32 m0, s27
	s_nop 0
	global_load_lds_dwordx4 v0, s[28:29]
	s_add_i32 m0, s27, 0x2000
	s_nop 0
	global_load_lds_dwordx4 v178, s[28:29]
	s_mov_b32 m0, s37
	s_nop 0
	global_load_lds_dwordx4 v182, s[94:95]
	s_mov_b32 m0, s38
	s_nop 0
	global_load_lds_dwordx4 v180, s[94:95]
	s_waitcnt vmcnt(8)
	s_waitcnt lgkmcnt(0)
	s_barrier
	s_setprio 1
	s_waitcnt lgkmcnt(0)
	v_mfma_f32_16x16x32_bf16 v[62:65], v[130:133], v[192:195], v[62:65]
	v_mfma_f32_16x16x32_bf16 v[58:61], v[138:141], v[192:195], v[58:61]
	v_mfma_f32_16x16x32_bf16 v[46:49], v[130:133], v[200:203], v[46:49]
	v_mfma_f32_16x16x32_bf16 v[42:45], v[138:141], v[200:203], v[42:45]
	v_mfma_f32_16x16x32_bf16 v[30:33], v[130:133], v[210:213], v[30:33]
	v_mfma_f32_16x16x32_bf16 v[26:29], v[138:141], v[210:213], v[26:29]
	v_mfma_f32_16x16x32_bf16 v[14:17], v[130:133], v[230:233], v[14:17]
	v_mfma_f32_16x16x32_bf16 v[10:13], v[138:141], v[230:233], v[10:13]
	v_mfma_f32_16x16x32_bf16 v[62:65], v[134:137], v[196:199], v[62:65]
	v_mfma_f32_16x16x32_bf16 v[58:61], v[142:145], v[196:199], v[58:61]
	v_mfma_f32_16x16x32_bf16 v[46:49], v[134:137], v[204:207], v[46:49]
	v_mfma_f32_16x16x32_bf16 v[42:45], v[142:145], v[204:207], v[42:45]
	v_mfma_f32_16x16x32_bf16 v[30:33], v[134:137], v[214:217], v[30:33]
	v_mfma_f32_16x16x32_bf16 v[26:29], v[142:145], v[214:217], v[26:29]
	v_mfma_f32_16x16x32_bf16 v[14:17], v[134:137], v[234:237], v[14:17]
	v_mfma_f32_16x16x32_bf16 v[10:13], v[142:145], v[234:237], v[10:13]
	s_setprio 0
	s_setprio 1
	v_mfma_f32_16x16x32_bf16 v[54:57], v[146:149], v[192:195], v[54:57]
	v_mfma_f32_16x16x32_bf16 v[50:53], v[154:157], v[192:195], v[50:53]
	v_mfma_f32_16x16x32_bf16 v[38:41], v[146:149], v[200:203], v[38:41]
	v_mfma_f32_16x16x32_bf16 v[34:37], v[154:157], v[200:203], v[34:37]
	v_mfma_f32_16x16x32_bf16 v[22:25], v[146:149], v[210:213], v[22:25]
	v_mfma_f32_16x16x32_bf16 v[18:21], v[154:157], v[210:213], v[18:21]
	v_mfma_f32_16x16x32_bf16 v[6:9], v[146:149], v[230:233], v[6:9]
	v_mfma_f32_16x16x32_bf16 v[2:5], v[154:157], v[230:233], v[2:5]
	v_mfma_f32_16x16x32_bf16 v[54:57], v[150:153], v[196:199], v[54:57]
	v_mfma_f32_16x16x32_bf16 v[50:53], v[158:161], v[196:199], v[50:53]
	v_mfma_f32_16x16x32_bf16 v[38:41], v[150:153], v[204:207], v[38:41]
	v_mfma_f32_16x16x32_bf16 v[34:37], v[158:161], v[204:207], v[34:37]
	v_mfma_f32_16x16x32_bf16 v[22:25], v[150:153], v[214:217], v[22:25]
	v_mfma_f32_16x16x32_bf16 v[18:21], v[158:161], v[214:217], v[18:21]
	v_mfma_f32_16x16x32_bf16 v[6:9], v[150:153], v[234:237], v[6:9]
	v_mfma_f32_16x16x32_bf16 v[2:5], v[158:161], v[234:237], v[2:5]
	s_setprio 0
	s_barrier
; #define PG8_STAGE(bufoff, gbase, voff) do { _Pragma("unroll") for (int _i = 0; _i < 2; ++_i) \
;         __builtin_amdgcn_global_load_lds((const unsigned*)((const char*)(gbase) + (voff)[_i]), (PG8_LAS unsigned*)(lds + (bufoff) + ldsw + _i * 8192), 16, 0, 0); } while (0)
; #define PG8_LDA(dst, b, h) do { _Pragma("unroll") for (int m = 0; m < 4; ++m) _Pragma("unroll") for (int k = 0; k < 2; ++k) dst[m][k] = *(const PG8_LAS bf16x8*)(lds + PG8_SA(b, h) + aoff + m * 2048 + k * 1024); } while (0)
; #define PG8_LDB(dst, b, h) do { _Pragma("unroll") for (int n = 0; n < 2; ++n) _Pragma("unroll") for (int k = 0; k < 2; ++k) dst[n][k] = *(const PG8_LAS bf16x8*)(lds + PG8_SB(b, h) + boff + n * 2048 + k * 1024); } while (0)
; #define PG8_MMA(ai, bj, At, Bt) do { __builtin_amdgcn_s_setprio(1); _Pragma("unroll") for (int m = 0; m < 4; ++m) _Pragma("unroll") for (int n = 0; n < 2; ++n) _Pragma("unroll") for (int k = 0; k < 2; ++k) \
;         acc[ai][bj][m][n] = __builtin_amdgcn_mfma_f32_16x16x32_bf16(Bt[n][k], At[m][k], acc[ai][bj][m][n], 0, 0, 0); __builtin_amdgcn_s_setprio(0); } while (0)
; #define PG8_WAIT_V(n) asm volatile("s_waitcnt vmcnt(" #n ")" ::: "memory")
; #define PG8_WAIT_L(n) asm volatile("s_waitcnt lgkmcnt(" #n ")" ::: "memory")
; #define PG8_BAR __builtin_amdgcn_s_barrier()
; #define PG8_SCHED __builtin_amdgcn_sched_barrier(0)
; template <class Epi, class Sched, bool ALIGN_EPI = false, bool SP2 = false>
; __device__ __forceinline__ void gemm_phase(PG8_LAS unsigned char* lds, const Gemm g, const Sched& S, const Epi& E) {
;     ...
;             PG8_LDB(B0, 1, 0); PG8_LDB(B1, 1, 1); PG8_SCHED; PG8_LDA(At, 1, 0); PG8_STAGE(PG8_SA(0, 1), a2 + hstep, voffA);
;             PG8_WAIT_V(8); PG8_WAIT_L(0); PG8_BAR; PG8_MMA(0, 0, At, B0); PG8_MMA(0, 1, At, B1); PG8_BAR; PG8_SCHED;
;             PG8_LDA(At, 1, 1); PG8_STAGE(PG8_SB(1, 0), b3, voffB); PG8_STAGE(PG8_SB(1, 1), b3 + hstep, voffB); PG8_STAGE(PG8_SA(1, 0), a3, voffA);
;             PG8_WAIT_V(8); PG8_WAIT_L(0); PG8_BAR; PG8_MMA(1, 0, At, B0); PG8_MMA(1, 1, At, B1); PG8_BAR; PG8_SCHED;
	s_add_i32 s27, 0, 0x18000
	s_add_i32 s45, 0, 0x1c000
	v_add_u32_e32 v142, s27, v227
	v_add_u32_e32 v158, s45, v227
	ds_read_b128 v[130:133], v142
	ds_read_b128 v[134:137], v142 offset:1024
	ds_read_b128 v[138:141], v142 offset:2048
	ds_read_b128 v[142:145], v142 offset:3072
	ds_read_b128 v[146:149], v158
	ds_read_b128 v[150:153], v158 offset:1024
	ds_read_b128 v[154:157], v158 offset:2048
	ds_read_b128 v[158:161], v158 offset:3072
	s_add_u32 s28, s94, 0x40000
	s_addc_u32 s29, s95, 0
	s_mov_b32 m0, s39
	ds_read_b128 v[192:195], v229 offset:32768
	ds_read_b128 v[196:199], v229 offset:33792
	ds_read_b128 v[200:203], v229 offset:34816
	ds_read_b128 v[204:207], v229 offset:35840
	ds_read_b128 v[210:213], v229 offset:36864
	ds_read_b128 v[214:217], v229 offset:37888
	ds_read_b128 v[230:233], v229 offset:38912
	ds_read_b128 v[234:237], v229 offset:39936
	global_load_lds_dwordx4 v182, s[28:29]
	s_mov_b32 m0, s47
	s_nop 0
	global_load_lds_dwordx4 v180, s[28:29]
	s_waitcnt vmcnt(8)
	s_waitcnt lgkmcnt(0)
	s_barrier
	s_setprio 1
	s_waitcnt lgkmcnt(0)
	v_mfma_f32_16x16x32_bf16 v[126:129], v[130:133], v[192:195], v[126:129]
	v_mfma_f32_16x16x32_bf16 v[122:125], v[138:141], v[192:195], v[122:125]
	v_mfma_f32_16x16x32_bf16 v[110:113], v[130:133], v[200:203], v[110:113]
	v_mfma_f32_16x16x32_bf16 v[106:109], v[138:141], v[200:203], v[106:109]
	v_mfma_f32_16x16x32_bf16 v[94:97], v[130:133], v[210:213], v[94:97]
	v_mfma_f32_16x16x32_bf16 v[90:93], v[138:141], v[210:213], v[90:93]
	v_mfma_f32_16x16x32_bf16 v[78:81], v[130:133], v[230:233], v[78:81]
	v_mfma_f32_16x16x32_bf16 v[74:77], v[138:141], v[230:233], v[74:77]
	v_mfma_f32_16x16x32_bf16 v[126:129], v[134:137], v[196:199], v[126:129]
	v_mfma_f32_16x16x32_bf16 v[122:125], v[142:145], v[196:199], v[122:125]
	v_mfma_f32_16x16x32_bf16 v[110:113], v[134:137], v[204:207], v[110:113]
	v_mfma_f32_16x16x32_bf16 v[106:109], v[142:145], v[204:207], v[106:109]
	v_mfma_f32_16x16x32_bf16 v[94:97], v[134:137], v[214:217], v[94:97]
	v_mfma_f32_16x16x32_bf16 v[90:93], v[142:145], v[214:217], v[90:93]
	v_mfma_f32_16x16x32_bf16 v[78:81], v[134:137], v[234:237], v[78:81]
	v_mfma_f32_16x16x32_bf16 v[74:77], v[142:145], v[234:237], v[74:77]
	s_setprio 0
	s_setprio 1
	v_mfma_f32_16x16x32_bf16 v[118:121], v[146:149], v[192:195], v[118:121]
	v_mfma_f32_16x16x32_bf16 v[114:117], v[154:157], v[192:195], v[114:117]
	v_mfma_f32_16x16x32_bf16 v[102:105], v[146:149], v[200:203], v[102:105]
	v_mfma_f32_16x16x32_bf16 v[98:101], v[154:157], v[200:203], v[98:101]
	v_mfma_f32_16x16x32_bf16 v[86:89], v[146:149], v[210:213], v[86:89]
	v_mfma_f32_16x16x32_bf16 v[82:85], v[154:157], v[210:213], v[82:85]
	v_mfma_f32_16x16x32_bf16 v[70:73], v[146:149], v[230:233], v[70:73]
	v_mfma_f32_16x16x32_bf16 v[66:69], v[154:157], v[230:233], v[66:69]
	v_mfma_f32_16x16x32_bf16 v[118:121], v[150:153], v[196:199], v[118:121]
	v_mfma_f32_16x16x32_bf16 v[114:117], v[158:161], v[196:199], v[114:117]
	v_mfma_f32_16x16x32_bf16 v[102:105], v[150:153], v[204:207], v[102:105]
	v_mfma_f32_16x16x32_bf16 v[98:101], v[158:161], v[204:207], v[98:101]
	v_mfma_f32_16x16x32_bf16 v[86:89], v[150:153], v[214:217], v[86:89]
	v_mfma_f32_16x16x32_bf16 v[82:85], v[158:161], v[214:217], v[82:85]
	v_mfma_f32_16x16x32_bf16 v[70:73], v[150:153], v[234:237], v[70:73]
	v_mfma_f32_16x16x32_bf16 v[66:69], v[158:161], v[234:237], v[66:69]
	s_setprio 0
	s_barrier
	s_add_i32 s27, s27, s36
	s_mov_b32 m0, s27
	ds_read_b128 v[192:195], v229 offset:49152
	ds_read_b128 v[196:199], v229 offset:50176
	ds_read_b128 v[200:203], v229 offset:51200
	ds_read_b128 v[204:207], v229 offset:52224
	ds_read_b128 v[210:213], v229 offset:53248
	ds_read_b128 v[214:217], v229 offset:54272
	ds_read_b128 v[230:233], v229 offset:55296
	ds_read_b128 v[234:237], v229 offset:56320
	s_add_u32 s100, s92, 0x80
	s_addc_u32 s101, s93, 0
	global_load_lds_dwordx4 v0, s[100:101]
	s_add_i32 m0, s27, 0x2000
	s_add_u32 s28, s92, 0x40080
	s_addc_u32 s29, s93, 0
	s_add_i32 s27, s45, s36
	s_add_u32 s100, s92, 0x80
	s_addc_u32 s101, s93, 0
	global_load_lds_dwordx4 v178, s[100:101]
	s_mov_b32 m0, s27
	s_nop 0
	global_load_lds_dwordx4 v0, s[28:29]
	s_add_i32 m0, s27, 0x2000
	s_nop 0
	global_load_lds_dwordx4 v178, s[28:29]
	s_mov_b32 m0, s59
	s_nop 0
	s_add_u32 s100, s94, 0x80
	s_addc_u32 s101, s95, 0
	global_load_lds_dwordx4 v182, s[100:101]
	s_mov_b32 m0, s60
	s_nop 0
	s_add_u32 s100, s94, 0x80
	s_addc_u32 s101, s95, 0
	global_load_lds_dwordx4 v180, s[100:101]
	s_waitcnt vmcnt(8)
	s_waitcnt lgkmcnt(0)
	s_barrier
	s_setprio 1
	s_waitcnt lgkmcnt(0)
	v_mfma_f32_16x16x32_bf16 v[62:65], v[130:133], v[192:195], v[62:65]
	v_mfma_f32_16x16x32_bf16 v[58:61], v[138:141], v[192:195], v[58:61]
	v_mfma_f32_16x16x32_bf16 v[46:49], v[130:133], v[200:203], v[46:49]
	v_mfma_f32_16x16x32_bf16 v[42:45], v[138:141], v[200:203], v[42:45]
	v_mfma_f32_16x16x32_bf16 v[30:33], v[130:133], v[210:213], v[30:33]
	v_mfma_f32_16x16x32_bf16 v[26:29], v[138:141], v[210:213], v[26:29]
	v_mfma_f32_16x16x32_bf16 v[14:17], v[130:133], v[230:233], v[14:17]
	v_mfma_f32_16x16x32_bf16 v[10:13], v[138:141], v[230:233], v[10:13]
	v_mfma_f32_16x16x32_bf16 v[62:65], v[134:137], v[196:199], v[62:65]
	v_mfma_f32_16x16x32_bf16 v[58:61], v[142:145], v[196:199], v[58:61]
	v_mfma_f32_16x16x32_bf16 v[46:49], v[134:137], v[204:207], v[46:49]
	v_mfma_f32_16x16x32_bf16 v[42:45], v[142:145], v[204:207], v[42:45]
	v_mfma_f32_16x16x32_bf16 v[30:33], v[134:137], v[214:217], v[30:33]
	v_mfma_f32_16x16x32_bf16 v[26:29], v[142:145], v[214:217], v[26:29]
	v_mfma_f32_16x16x32_bf16 v[14:17], v[134:137], v[234:237], v[14:17]
	v_mfma_f32_16x16x32_bf16 v[10:13], v[142:145], v[234:237], v[10:13]
	s_setprio 0
	s_setprio 1
	v_mfma_f32_16x16x32_bf16 v[54:57], v[146:149], v[192:195], v[54:57]
	v_mfma_f32_16x16x32_bf16 v[50:53], v[154:157], v[192:195], v[50:53]
	v_mfma_f32_16x16x32_bf16 v[38:41], v[146:149], v[200:203], v[38:41]
	v_mfma_f32_16x16x32_bf16 v[34:37], v[154:157], v[200:203], v[34:37]
	v_mfma_f32_16x16x32_bf16 v[22:25], v[146:149], v[210:213], v[22:25]
	v_mfma_f32_16x16x32_bf16 v[18:21], v[154:157], v[210:213], v[18:21]
	v_mfma_f32_16x16x32_bf16 v[6:9], v[146:149], v[230:233], v[6:9]
	v_mfma_f32_16x16x32_bf16 v[2:5], v[154:157], v[230:233], v[2:5]
	v_mfma_f32_16x16x32_bf16 v[54:57], v[150:153], v[196:199], v[54:57]
	v_mfma_f32_16x16x32_bf16 v[50:53], v[158:161], v[196:199], v[50:53]
	v_mfma_f32_16x16x32_bf16 v[38:41], v[150:153], v[204:207], v[38:41]
	v_mfma_f32_16x16x32_bf16 v[34:37], v[158:161], v[204:207], v[34:37]
	v_mfma_f32_16x16x32_bf16 v[22:25], v[150:153], v[214:217], v[22:25]
	v_mfma_f32_16x16x32_bf16 v[18:21], v[158:161], v[214:217], v[18:21]
	v_mfma_f32_16x16x32_bf16 v[6:9], v[150:153], v[234:237], v[6:9]
	v_mfma_f32_16x16x32_bf16 v[2:5], v[158:161], v[234:237], v[2:5]
	s_setprio 0
	s_barrier
	s_add_i32 s26, s26, 2
	s_add_u32 s90, s90, 0x100
	s_addc_u32 s91, s91, 0
	s_add_u32 s64, s64, 0x100
	s_addc_u32 s65, s65, 0
	s_cmp_gt_u32 s26, 13
	s_cbranch_scc0 .LBB0_752
	s_and_b64 vcc, exec, s[78:79]
	s_cbranch_vccz .LBB0_755
	s_barrier

; __global__ void __launch_bounds__(NTHREADS, 2) hymba_fwd(Args a) {
	.amdhsa_kernel _Z9hymba_fwd4Args
		.amdhsa_group_segment_fixed_size 0
		.amdhsa_private_segment_fixed_size 0
		.amdhsa_kernarg_size 488
		.amdhsa_user_sgpr_count 2
		.amdhsa_user_sgpr_dispatch_ptr 0
		.amdhsa_user_sgpr_queue_ptr 0
		.amdhsa_user_sgpr_kernarg_segment_ptr 1
		.amdhsa_user_sgpr_dispatch_id 0
		.amdhsa_user_sgpr_kernarg_preload_length 0
		.amdhsa_user_sgpr_kernarg_preload_offset 0
		.amdhsa_user_sgpr_private_segment_size 0
		.amdhsa_uses_dynamic_stack 0
		.amdhsa_enable_private_segment 0
		.amdhsa_system_sgpr_workgroup_id_x 1
		.amdhsa_system_sgpr_workgroup_id_y 0
		.amdhsa_system_sgpr_workgroup_id_z 0
		.amdhsa_system_sgpr_workgroup_info 0
		.amdhsa_system_vgpr_workitem_id 2
		.amdhsa_next_free_vgpr 255
		.amdhsa_next_free_sgpr 102
		.amdhsa_accum_offset 256
		.amdhsa_reserve_vcc 1
		.amdhsa_float_round_mode_32 0
		.amdhsa_float_round_mode_16_64 0
		.amdhsa_float_denorm_mode_32 3
		.amdhsa_float_denorm_mode_16_64 3
		.amdhsa_dx10_clamp 1
		.amdhsa_ieee_mode 1
		.amdhsa_fp16_overflow 0
		.amdhsa_tg_split 0
		.amdhsa_exception_fp_ieee_invalid_op 0
		.amdhsa_exception_fp_denorm_src 0
		.amdhsa_exception_fp_ieee_div_zero 0
		.amdhsa_exception_fp_ieee_overflow 0
		.amdhsa_exception_fp_ieee_underflow 0
		.amdhsa_exception_fp_ieee_inexact 0
		.amdhsa_exception_int_div_zero 0
	.end_amdhsa_kernel

; __global__ void __launch_bounds__(NTHREADS, 2) hymba_fwd(Args a) {
amdhsa.kernels:
  - .agpr_count:     0
    .args:
      - .offset:         0
        .size:           232
        .value_kind:     by_value
      - .offset:         232
        .size:           4
        .value_kind:     hidden_block_count_x
      - .offset:         236
        .size:           4
        .value_kind:     hidden_block_count_y
      - .offset:         240
        .size:           4
        .value_kind:     hidden_block_count_z
      - .offset:         244
        .size:           2
        .value_kind:     hidden_group_size_x
      - .offset:         246
        .size:           2
        .value_kind:     hidden_group_size_y
      - .offset:         248
        .size:           2
        .value_kind:     hidden_group_size_z
      - .offset:         250
        .size:           2
        .value_kind:     hidden_remainder_x
      - .offset:         252
        .size:           2
        .value_kind:     hidden_remainder_y
      - .offset:         254
        .size:           2
        .value_kind:     hidden_remainder_z
      - .offset:         272
        .size:           8
        .value_kind:     hidden_global_offset_x
      - .offset:         280
        .size:           8
        .value_kind:     hidden_global_offset_y
      - .offset:         288
        .size:           8
        .value_kind:     hidden_global_offset_z
      - .offset:         296
        .size:           2
        .value_kind:     hidden_grid_dims
      - .offset:         320
        .size:           8
        .value_kind:     hidden_multigrid_sync_arg
      - .offset:         352
        .size:           4
        .value_kind:     hidden_dynamic_lds_size
    .group_segment_fixed_size: 0
    .kernarg_segment_align: 8
    .kernarg_segment_size: 488
    .language:       OpenCL C
    .language_version:
      - 2
      - 0
    .max_flat_workgroup_size: 512
    .name:           _Z9hymba_fwd4Args
    .private_segment_fixed_size: 0
    .sgpr_count:     108
    .sgpr_spill_count: 33
    .symbol:         _Z9hymba_fwd4Args.kd
    .uniform_work_group_size: 1
    .uses_dynamic_stack: false
    .vgpr_count:     255
    .vgpr_spill_count: 0
    .wavefront_size: 64
